# counted waits across the tile boundary: first two K-loop phases after an epilogue no longer wait for that epilogue's stores
# baseline (speedup 1.0000x reference)
; #define PG8_STAGE(bufoff, gbase, voff) do { _Pragma("unroll") for (int _i = 0; _i < 2; ++_i) \
;         __builtin_amdgcn_global_load_lds((const unsigned*)((const char*)(gbase) + (voff)[_i]), (LAS unsigned*)(lds + (bufoff) + ldsw + _i * 8192), 16, 0, 0); } while (0)
; #define PG8_BAR __builtin_amdgcn_s_barrier()
; template <class Epi>
; __device__ __forceinline__ void gemm_phase(LAS unsigned char* lds, const Gemm g, const StaticOrder& S, const Epi& E, const int tid) {
;     const int wid = __builtin_amdgcn_readfirstlane(tid >> 6), lane = tid & 63, wr = wid >> 2, wc = wid & 3, fr = lane & 15, fq = lane >> 4;
;     const int K = g.K, nt = K / BK;
;     unsigned voffA[2], voffB[2];
; #pragma unroll
;     for (int i = 0; i < 2; ++i) { int R, C; stage_rc(tid * 16 + i * 8192, R, C); const int Rb = Epi::PERM ? ((R & ~31) + perm32(R & 31)) : R;
;         voffA[i] = (unsigned)(R * g.lda + C) * 2u; voffB[i] = (unsigned)(Rb * g.ldb + C) * 2u; }
;     const size_t kstep = (size_t)(BK * 2);
;     const size_t hstepA = (size_t)HALF * g.lda * 2, hstepB = (size_t)HALF * g.ldb * 2;
;     const size_t tstepA = 2 * hstepA, tstepB = 2 * hstepB;
;     const unsigned ldsw = (unsigned)wid * 1024u;
;     const int aoff = lds_byte(wr * 64 + fr, fq * 8), boff = lds_byte(wc * 32 + fr, fq * 8);
;     ...
;     Unit cur, nxt; int ui = 0;
;     if (!S.next(0, cur)) return;
;     f32x4 acc[2][2][4][2];
; #pragma unroll
;     for (int a = 0; a < 2; ++a)
; #pragma unroll
;         for (int b = 0; b < 2; ++b)
; #pragma unroll
;             for (int m = 0; m < 4; ++m)
; #pragma unroll
;                 for (int n = 0; n < 2; ++n) acc[a][b][m][n] = (f32x4){0.f, 0.f, 0.f, 0.f};
;     bf16x8 At[4][2], B0[2][2], B1[2][2];
;     const char* cA = (const char*)g.A + (size_t)cur.pm * tstepA + (size_t)cur.half * K * 2; const char* cB = (const char*)g.Bt + (size_t)cur.pn * tstepB + (size_t)cur.half * K * 2;
;     PG8_STAGE(PG8_SB(0, 0), cB, voffB); PG8_STAGE(PG8_SB(0, 1), cB + hstepB, voffB); PG8_STAGE(PG8_SA(0, 0), cA, voffA); PG8_STAGE(PG8_SA(0, 1), cA + hstepA, voffA);
;     if (wr == 1) PG8_BAR;
.LBB0_22:
	v_readlane_b32 s4, v248, 12
	v_readlane_b32 s5, v248, 13
	s_andn2_b64 vcc, exec, s[4:5]
	v_readfirstlane_b32 s4, v188
	s_cbranch_vccnz .LBB0_92
	s_mov_b32 s98, 0
	v_lshlrev_b32_e32 v0, 4, v188
	v_add_u32_e32 v1, 0x2000, v0
	v_ashrrev_i32_e32 v2, 31, v1
	v_lshrrev_b32_e32 v2, 22, v2
	v_add_u32_e32 v2, v1, v2
	v_ashrrev_i32_e32 v8, 10, v2
	v_readlane_b32 s6, v248, 4
	v_mul_i32_i24_e32 v2, 0x400, v8
	v_readlane_b32 s7, v248, 5
	v_sub_u32_e32 v1, v1, v2
	s_load_dwordx2 s[6:7], s[6:7], 0xb8
	v_lshrrev_b32_e32 v2, 4, v1
	v_bitop3_b32 v1, v2, v1, 32 bitop3:0x6c
	v_ashrrev_i32_e32 v2, 31, v1
	v_lshrrev_b32_e32 v2, 26, v2
	v_add_u32_e32 v2, v1, v2
	v_lshlrev_b32_e32 v3, 3, v8
	s_waitcnt lgkmcnt(0)
	s_add_u32 s34, s6, 0x4100000
	v_ashrrev_i32_e32 v9, 6, v2
	v_and_b32_e32 v3, -16, v3
	s_addc_u32 s35, s7, 0
	v_add_u32_e32 v3, v9, v3
	s_add_u32 s36, s6, 0x3100000
	v_and_b32_e32 v4, 3, v9
	s_mov_b32 s6, 0xfffe0
	v_lshrrev_b32_e32 v5, 2, v3
	v_lshlrev_b32_e32 v6, 1, v3
	v_and_b32_e32 v2, 0xc0, v2
	v_and_or_b32 v4, v3, s6, v4
	v_and_b32_e32 v5, 4, v5
	v_and_b32_e32 v6, 24, v6
	v_sub_u32_e32 v1, v1, v2
	v_or3_b32 v4, v4, v5, v6
	v_lshlrev_b32_e32 v5, 5, v8
	v_ashrrev_i16_sdwa v1, v208, sext(v1) dst_sel:DWORD dst_unused:UNUSED_PAD src0_sel:DWORD src1_sel:BYTE_0
	v_and_b32_e32 v5, 32, v5
	v_bfe_i32 v10, v1, 0, 16
	v_add_lshl_u32 v1, v5, v10, 1
	v_lshl_add_u32 v162, v4, 12, v1
	v_lshl_add_u32 v164, v3, 12, v1
	v_bfe_i32 v1, v188, 27, 1
	v_lshrrev_b32_e32 v1, 22, v1
	v_add_u32_e32 v1, v0, v1
	v_and_b32_e32 v1, 0xfffffc00, v1
	v_sub_u32_e32 v0, v0, v1
	v_lshrrev_b32_e32 v1, 4, v0
	v_ashrrev_i32_e32 v2, 31, v188
	v_bitop3_b32 v0, v1, v0, 32 bitop3:0x6c
	v_lshrrev_b32_e32 v2, 26, v2
	v_ashrrev_i32_e32 v1, 31, v0
	v_add_u32_e32 v2, v188, v2
	v_lshrrev_b32_e32 v1, 26, v1
	v_ashrrev_i32_e32 v12, 6, v2
	v_add_u32_e32 v1, v0, v1
	v_lshlrev_b32_e32 v2, 3, v12
	v_ashrrev_i32_e32 v11, 6, v1
	v_and_b32_e32 v2, -16, v2
	v_add_u32_e32 v2, v11, v2
	v_and_b32_e32 v3, 3, v11
	v_lshrrev_b32_e32 v4, 2, v2
	v_lshlrev_b32_e32 v5, 1, v2
	v_and_b32_e32 v1, 0xc0, v1
	s_addc_u32 s37, s7, 0
	s_ashr_i32 s5, s4, 6
	v_and_or_b32 v3, v2, s6, v3
	v_and_b32_e32 v4, 4, v4
	v_and_b32_e32 v5, 24, v5
	v_sub_u32_e32 v0, v0, v1
	s_ashr_i32 s12, s4, 8
	s_lshl_b32 s39, s5, 10
	v_or3_b32 v3, v3, v4, v5
	v_lshlrev_b32_e32 v4, 5, v12
	v_ashrrev_i16_sdwa v0, v208, sext(v0) dst_sel:DWORD dst_unused:UNUSED_PAD src0_sel:DWORD src1_sel:BYTE_0
	v_readlane_b32 s6, v247, 18
	v_and_b32_e32 v4, 32, v4
	v_bfe_i32 v13, v0, 0, 16
	v_readlane_b32 s7, v247, 19
	s_add_u32 s28, s36, s6
	v_add_lshl_u32 v0, v4, v13, 1
	s_addc_u32 s29, s37, s7
	s_add_i32 s40, s39, 0
	v_lshl_add_u32 v136, v3, 12, v0
	s_add_i32 m0, s40, 0x10000
	v_lshl_add_u32 v166, v2, 12, v0
	global_load_lds_dwordx4 v136, s[28:29]
	s_add_i32 m0, s40, 0x12000
	s_add_u32 s6, s28, 0x80000
	global_load_lds_dwordx4 v162, s[28:29]
	s_addc_u32 s7, s29, 0
	s_add_i32 m0, s40, 0x14000
	v_mov_b32_e32 v163, v137
	global_load_lds_dwordx4 v136, s[6:7]
	s_add_i32 m0, s40, 0x16000
	v_mov_b32_e32 v167, v137
	global_load_lds_dwordx4 v162, s[6:7]
	v_readlane_b32 s6, v247, 22
	v_readlane_b32 s7, v247, 23
	s_add_u32 s6, s34, s6
	s_addc_u32 s7, s35, s7
	s_add_i32 s41, s40, 0x2000
	s_mov_b32 m0, s40
	s_add_u32 s8, s6, 0x80000
	global_load_lds_dwordx4 v166, s[6:7]
	s_mov_b32 m0, s41
	s_addc_u32 s9, s7, 0
	s_add_i32 s42, s40, 0x4000
	global_load_lds_dwordx4 v164, s[6:7]
	s_mov_b32 m0, s42
	s_add_i32 s43, s40, 0x6000
	global_load_lds_dwordx4 v166, s[8:9]
	s_mov_b32 m0, s43
	v_mov_b32_e32 v165, v137
	global_load_lds_dwordx4 v164, s[8:9]
	s_cmp_eq_u32 s12, 1
	v_lshl_add_u64 v[6:7], s[28:29], 0, v[136:137]
	v_lshl_add_u64 v[4:5], s[28:29], 0, v[162:163]
	v_lshl_add_u64 v[0:1], s[6:7], 0, v[166:167]
	s_cselect_b64 s[8:9], -1, 0
	s_cmp_lg_u32 s12, 1
	v_lshl_add_u64 v[2:3], s[6:7], 0, v[164:165]
	s_cbranch_scc1 .LBB0_25
	s_barrier

; #define PG8_STAGE(bufoff, gbase, voff) do { _Pragma("unroll") for (int _i = 0; _i < 2; ++_i) \
;         __builtin_amdgcn_global_load_lds((const unsigned*)((const char*)(gbase) + (voff)[_i]), (LAS unsigned*)(lds + (bufoff) + ldsw + _i * 8192), 16, 0, 0); } while (0)
; #define PG8_LDA(dst, b, h) do { _Pragma("unroll") for (int m = 0; m < 4; ++m) _Pragma("unroll") for (int k = 0; k < 2; ++k) dst[m][k] = *(const LAS bf16x8*)(lds + PG8_SA(b, h) + aoff + m * 2048 + k * 1024); } while (0)
; #define PG8_LDB(dst, b, h) do { _Pragma("unroll") for (int n = 0; n < 2; ++n) _Pragma("unroll") for (int k = 0; k < 2; ++k) dst[n][k] = *(const LAS bf16x8*)(lds + PG8_SB(b, h) + boff + n * 2048 + k * 1024); } while (0)
; #define PG8_MMA(ai, bj, At, Bt) do { __builtin_amdgcn_s_setprio(1); _Pragma("unroll") for (int m = 0; m < 4; ++m) _Pragma("unroll") for (int n = 0; n < 2; ++n) _Pragma("unroll") for (int k = 0; k < 2; ++k) \
;         acc[ai][bj][m][n] = __builtin_amdgcn_mfma_f32_16x16x32_bf16(Bt[n][k], At[m][k], acc[ai][bj][m][n], 0, 0, 0); __builtin_amdgcn_s_setprio(0); } while (0)
; #define PG8_WAIT_V(n) asm volatile("s_waitcnt vmcnt(" #n ")" ::: "memory")
; #define PG8_WAIT_L(n) asm volatile("s_waitcnt lgkmcnt(" #n ")" ::: "memory")
; #define PG8_BAR __builtin_amdgcn_s_barrier()
; #define PG8_SCHED __builtin_amdgcn_sched_barrier(0)
; template <class Epi>
; __device__ __forceinline__ void gemm_phase(LAS unsigned char* lds, const Gemm g, const StaticOrder& S, const Epi& E, const int tid) {
;     ...
;         for (int t = 0; t < nt; t += 2) {
;             const bool last = (t == nt - 2);
;             const char* a1 = cA + (size_t)(t + 1) * kstep;
;             const char* a2 = last ? nA : cA + (size_t)(t + 2) * kstep; const char* b2 = last ? nB : cB + (size_t)(t + 2) * kstep;
;             const char* a3 = a2 + kstep; const char* b3 = b2 + kstep;
;             PG8_LDB(B0, 0, 0); PG8_LDB(B1, 0, 1); PG8_SCHED; PG8_LDA(At, 0, 0); PG8_STAGE(PG8_SA(1, 1), a1 + hstepA, voffA);
;             PG8_WAIT_V(8); PG8_WAIT_L(0); PG8_BAR; PG8_MMA(0, 0, At, B0); PG8_MMA(0, 1, At, B1); PG8_BAR; PG8_SCHED;
;             PG8_LDA(At, 0, 1); PG8_STAGE(PG8_SB(0, 0), b2, voffB); PG8_STAGE(PG8_SB(0, 1), b2 + hstepB, voffB); PG8_STAGE(PG8_SA(0, 0), a2, voffA);
;             PG8_WAIT_V(8); PG8_WAIT_L(0); PG8_BAR; PG8_MMA(1, 0, At, B0); PG8_MMA(1, 1, At, B1); PG8_BAR; PG8_SCHED;
.LBB0_35:
	s_add_u32 s28, s6, 0xfff80080
	s_addc_u32 s29, s7, -1
	s_add_i32 s54, 0, 0x10000
	s_cmp_eq_u32 s53, 12
	s_cselect_b32 s31, s15, s29
	s_cselect_b32 s30, s21, s28
	s_cselect_b32 s29, s19, s52
	s_cselect_b32 s28, s50, s51
	s_add_i32 s68, 0, 0x14000
	v_add_u32_e32 v100, s54, v189
	v_add_u32_e32 v158, s68, v189
	ds_read_b128 v[64:67], v100
	ds_read_b128 v[76:79], v100 offset:1024
	ds_read_b128 v[88:91], v100 offset:2048
	ds_read_b128 v[100:103], v100 offset:3072
	ds_read_b128 v[146:149], v158
	ds_read_b128 v[150:153], v158 offset:1024
	ds_read_b128 v[154:157], v158 offset:2048
	ds_read_b128 v[158:161], v158 offset:3072
	v_lshl_add_u64 v[176:177], s[6:7], 0, v[168:169]
	s_add_i32 m0, s40, 0xc000
	ds_read_b128 v[172:175], v193
	ds_read_b128 v[194:197], v193 offset:1024
	ds_read_b128 v[198:201], v193 offset:2048
	ds_read_b128 v[216:219], v193 offset:3072
	ds_read_b128 v[220:223], v193 offset:4096
	ds_read_b128 v[224:227], v193 offset:5120
	ds_read_b128 v[228:231], v193 offset:6144
	ds_read_b128 v[232:235], v193 offset:7168
	global_load_lds_dwordx4 v[176:177], off
	v_lshl_add_u64 v[176:177], s[6:7], 0, v[170:171]
	s_add_i32 m0, s40, 0xe000
	s_nop 0
	global_load_lds_dwordx4 v[176:177], off
	s_cmp_lg_u32 s98, 0
	s_cbranch_scc1 .Ltb_g20r
	s_waitcnt vmcnt(8)
	s_branch .Ltb_g20d
.Ltb_g20r:
	s_waitcnt vmcnt(24)
.Ltb_g20d:
	s_waitcnt lgkmcnt(0)
	s_barrier
	s_setprio 1
	s_waitcnt lgkmcnt(0)
	v_mfma_f32_16x16x32_bf16 v[142:145], v[64:67], v[172:175], v[142:145]
	v_mfma_f32_16x16x32_bf16 v[138:141], v[88:91], v[172:175], v[138:141]
	v_mfma_f32_16x16x32_bf16 v[124:127], v[64:67], v[198:201], v[124:127]
	v_mfma_f32_16x16x32_bf16 v[120:123], v[88:91], v[198:201], v[120:123]
	v_mfma_f32_16x16x32_bf16 v[108:111], v[64:67], v[220:223], v[108:111]
	v_mfma_f32_16x16x32_bf16 v[104:107], v[88:91], v[220:223], v[104:107]
	v_mfma_f32_16x16x32_bf16 v[84:87], v[64:67], v[228:231], v[84:87]
	v_mfma_f32_16x16x32_bf16 v[80:83], v[88:91], v[228:231], v[80:83]
	v_mfma_f32_16x16x32_bf16 v[142:145], v[76:79], v[194:197], v[142:145]
	v_mfma_f32_16x16x32_bf16 v[138:141], v[100:103], v[194:197], v[138:141]
	v_mfma_f32_16x16x32_bf16 v[124:127], v[76:79], v[216:219], v[124:127]
	v_mfma_f32_16x16x32_bf16 v[120:123], v[100:103], v[216:219], v[120:123]
	v_mfma_f32_16x16x32_bf16 v[108:111], v[76:79], v[224:227], v[108:111]
	v_mfma_f32_16x16x32_bf16 v[104:107], v[100:103], v[224:227], v[104:107]
	v_mfma_f32_16x16x32_bf16 v[84:87], v[76:79], v[232:235], v[84:87]
	v_mfma_f32_16x16x32_bf16 v[80:83], v[100:103], v[232:235], v[80:83]
	s_setprio 0
	s_setprio 1
	v_mfma_f32_16x16x32_bf16 v[132:135], v[146:149], v[172:175], v[132:135]
	v_mfma_f32_16x16x32_bf16 v[128:131], v[154:157], v[172:175], v[128:131]
	v_mfma_f32_16x16x32_bf16 v[116:119], v[146:149], v[198:201], v[116:119]
	v_mfma_f32_16x16x32_bf16 v[112:115], v[154:157], v[198:201], v[112:115]
	v_mfma_f32_16x16x32_bf16 v[96:99], v[146:149], v[220:223], v[96:99]
	v_mfma_f32_16x16x32_bf16 v[92:95], v[154:157], v[220:223], v[92:95]
	v_mfma_f32_16x16x32_bf16 v[72:75], v[146:149], v[228:231], v[72:75]
	v_mfma_f32_16x16x32_bf16 v[68:71], v[154:157], v[228:231], v[68:71]
	v_mfma_f32_16x16x32_bf16 v[132:135], v[150:153], v[194:197], v[132:135]
	v_mfma_f32_16x16x32_bf16 v[128:131], v[158:161], v[194:197], v[128:131]
	v_mfma_f32_16x16x32_bf16 v[116:119], v[150:153], v[216:219], v[116:119]
	v_mfma_f32_16x16x32_bf16 v[112:115], v[158:161], v[216:219], v[112:115]
	v_mfma_f32_16x16x32_bf16 v[96:99], v[150:153], v[224:227], v[96:99]
	v_mfma_f32_16x16x32_bf16 v[92:95], v[158:161], v[224:227], v[92:95]
	v_mfma_f32_16x16x32_bf16 v[72:75], v[150:153], v[232:235], v[72:75]
	v_mfma_f32_16x16x32_bf16 v[68:71], v[158:161], v[232:235], v[68:71]
	s_setprio 0
	s_barrier
	s_add_i32 s54, s54, s39
	v_lshl_add_u64 v[176:177], s[28:29], 0, v[136:137]
	s_mov_b32 m0, s54
	ds_read_b128 v[172:175], v193 offset:16384
	ds_read_b128 v[194:197], v193 offset:17408
	ds_read_b128 v[198:201], v193 offset:18432
	ds_read_b128 v[216:219], v193 offset:19456
	ds_read_b128 v[220:223], v193 offset:20480
	ds_read_b128 v[224:227], v193 offset:21504
	ds_read_b128 v[228:231], v193 offset:22528
	ds_read_b128 v[232:235], v193 offset:23552
	global_load_lds_dwordx4 v[176:177], off
	s_add_i32 m0, s54, 0x2000
	s_add_u32 s54, s28, 0x80000
	v_lshl_add_u64 v[190:191], s[28:29], 0, v[162:163]
	s_addc_u32 s55, s29, 0
	s_add_i32 s68, s68, s39
	global_load_lds_dwordx4 v[190:191], off
	v_lshl_add_u64 v[202:203], s[54:55], 0, v[136:137]
	s_mov_b32 m0, s68
	v_lshl_add_u64 v[236:237], s[30:31], 0, v[164:165]
	global_load_lds_dwordx4 v[202:203], off
	v_lshl_add_u64 v[202:203], s[54:55], 0, v[162:163]
	s_add_i32 m0, s68, 0x2000
	s_nop 0
	global_load_lds_dwordx4 v[202:203], off
	v_lshl_add_u64 v[202:203], s[30:31], 0, v[166:167]
	s_mov_b32 m0, s40
	s_nop 0
	global_load_lds_dwordx4 v[202:203], off
	s_mov_b32 m0, s41
	s_nop 0
	global_load_lds_dwordx4 v[236:237], off
	s_cmp_lg_u32 s98, 0
	s_cbranch_scc1 .Ltb_g21r
	s_waitcnt vmcnt(8)
	s_branch .Ltb_g21d

; #define PG8_STAGE(bufoff, gbase, voff) do { _Pragma("unroll") for (int _i = 0; _i < 2; ++_i) \
;         __builtin_amdgcn_global_load_lds((const unsigned*)((const char*)(gbase) + (voff)[_i]), (LAS unsigned*)(lds + (bufoff) + ldsw + _i * 8192), 16, 0, 0); } while (0)
; #define PG8_LDA(dst, b, h) do { _Pragma("unroll") for (int m = 0; m < 4; ++m) _Pragma("unroll") for (int k = 0; k < 2; ++k) dst[m][k] = *(const LAS bf16x8*)(lds + PG8_SA(b, h) + aoff + m * 2048 + k * 1024); } while (0)
; #define PG8_LDB(dst, b, h) do { _Pragma("unroll") for (int n = 0; n < 2; ++n) _Pragma("unroll") for (int k = 0; k < 2; ++k) dst[n][k] = *(const LAS bf16x8*)(lds + PG8_SB(b, h) + boff + n * 2048 + k * 1024); } while (0)
; #define PG8_MMA(ai, bj, At, Bt) do { __builtin_amdgcn_s_setprio(1); _Pragma("unroll") for (int m = 0; m < 4; ++m) _Pragma("unroll") for (int n = 0; n < 2; ++n) _Pragma("unroll") for (int k = 0; k < 2; ++k) \
;         acc[ai][bj][m][n] = __builtin_amdgcn_mfma_f32_16x16x32_bf16(Bt[n][k], At[m][k], acc[ai][bj][m][n], 0, 0, 0); __builtin_amdgcn_s_setprio(0); } while (0)
; #define PG8_WAIT_V(n) asm volatile("s_waitcnt vmcnt(" #n ")" ::: "memory")
; #define PG8_WAIT_L(n) asm volatile("s_waitcnt lgkmcnt(" #n ")" ::: "memory")
; #define PG8_BAR __builtin_amdgcn_s_barrier()
; #define PG8_SCHED __builtin_amdgcn_sched_barrier(0)
; template <class Epi>
; __device__ __forceinline__ void gemm_phase(LAS unsigned char* lds, const Gemm g, const StaticOrder& S, const Epi& E, const int tid) {
;     ...
;             PG8_WAIT_V(8); PG8_WAIT_L(0); PG8_BAR; PG8_MMA(1, 0, At, B0); PG8_MMA(1, 1, At, B1); PG8_BAR; PG8_SCHED;
;             PG8_LDB(B0, 1, 0); PG8_LDB(B1, 1, 1); PG8_SCHED; PG8_LDA(At, 1, 0); PG8_STAGE(PG8_SA(0, 1), a2 + hstepA, voffA);
;             PG8_WAIT_V(8); PG8_WAIT_L(0); PG8_BAR; PG8_MMA(0, 0, At, B0); PG8_MMA(0, 1, At, B1); PG8_BAR; PG8_SCHED;
.Ltb_g21d:
	s_mov_b32 s98, 0
	s_waitcnt lgkmcnt(0)
	s_barrier
	s_setprio 1
	s_waitcnt lgkmcnt(0)
	v_mfma_f32_16x16x32_bf16 v[60:63], v[64:67], v[172:175], v[60:63]
	v_mfma_f32_16x16x32_bf16 v[56:59], v[88:91], v[172:175], v[56:59]
	v_mfma_f32_16x16x32_bf16 v[44:47], v[64:67], v[198:201], v[44:47]
	v_mfma_f32_16x16x32_bf16 v[40:43], v[88:91], v[198:201], v[40:43]
	v_mfma_f32_16x16x32_bf16 v[28:31], v[64:67], v[220:223], v[28:31]
	v_mfma_f32_16x16x32_bf16 v[24:27], v[88:91], v[220:223], v[24:27]
	v_mfma_f32_16x16x32_bf16 v[12:15], v[64:67], v[228:231], v[12:15]
	v_mfma_f32_16x16x32_bf16 v[8:11], v[88:91], v[228:231], v[8:11]
	v_mfma_f32_16x16x32_bf16 v[60:63], v[76:79], v[194:197], v[60:63]
	v_mfma_f32_16x16x32_bf16 v[56:59], v[100:103], v[194:197], v[56:59]
	v_mfma_f32_16x16x32_bf16 v[44:47], v[76:79], v[216:219], v[44:47]
	v_mfma_f32_16x16x32_bf16 v[40:43], v[100:103], v[216:219], v[40:43]
	v_mfma_f32_16x16x32_bf16 v[28:31], v[76:79], v[224:227], v[28:31]
	v_mfma_f32_16x16x32_bf16 v[24:27], v[100:103], v[224:227], v[24:27]
	v_mfma_f32_16x16x32_bf16 v[12:15], v[76:79], v[232:235], v[12:15]
	v_mfma_f32_16x16x32_bf16 v[8:11], v[100:103], v[232:235], v[8:11]
	s_setprio 0
	s_setprio 1
	v_mfma_f32_16x16x32_bf16 v[52:55], v[146:149], v[172:175], v[52:55]
	v_mfma_f32_16x16x32_bf16 v[48:51], v[154:157], v[172:175], v[48:51]
	v_mfma_f32_16x16x32_bf16 v[36:39], v[146:149], v[198:201], v[36:39]
	v_mfma_f32_16x16x32_bf16 v[32:35], v[154:157], v[198:201], v[32:35]
	v_mfma_f32_16x16x32_bf16 v[20:23], v[146:149], v[220:223], v[20:23]
	v_mfma_f32_16x16x32_bf16 v[16:19], v[154:157], v[220:223], v[16:19]
	v_mfma_f32_16x16x32_bf16 v[4:7], v[146:149], v[228:231], v[4:7]
	v_mfma_f32_16x16x32_bf16 v[0:3], v[154:157], v[228:231], v[0:3]
	v_mfma_f32_16x16x32_bf16 v[52:55], v[150:153], v[194:197], v[52:55]
	v_mfma_f32_16x16x32_bf16 v[48:51], v[158:161], v[194:197], v[48:51]
	v_mfma_f32_16x16x32_bf16 v[36:39], v[150:153], v[216:219], v[36:39]
	v_mfma_f32_16x16x32_bf16 v[32:35], v[158:161], v[216:219], v[32:35]
	v_mfma_f32_16x16x32_bf16 v[20:23], v[150:153], v[224:227], v[20:23]
	v_mfma_f32_16x16x32_bf16 v[16:19], v[158:161], v[224:227], v[16:19]
	v_mfma_f32_16x16x32_bf16 v[4:7], v[150:153], v[232:235], v[4:7]
	v_mfma_f32_16x16x32_bf16 v[0:3], v[158:161], v[232:235], v[0:3]
	s_setprio 0
	s_barrier
	s_add_i32 s54, 0, 0x18000
	s_add_i32 s55, 0, 0x1c000
	v_add_u32_e32 v100, s54, v189
	v_add_u32_e32 v158, s55, v189
	ds_read_b128 v[64:67], v100
	ds_read_b128 v[76:79], v100 offset:1024
	ds_read_b128 v[88:91], v100 offset:2048
	ds_read_b128 v[100:103], v100 offset:3072
	ds_read_b128 v[146:149], v158
	ds_read_b128 v[150:153], v158 offset:1024
	ds_read_b128 v[154:157], v158 offset:2048
	ds_read_b128 v[158:161], v158 offset:3072
	s_add_u32 s30, s30, 0x80000
	s_addc_u32 s31, s31, 0
	s_mov_b32 m0, s42
	v_lshl_add_u64 v[238:239], s[30:31], 0, v[166:167]
	ds_read_b128 v[172:175], v193 offset:32768
	ds_read_b128 v[194:197], v193 offset:33792
	ds_read_b128 v[198:201], v193 offset:34816
	ds_read_b128 v[216:219], v193 offset:35840
	ds_read_b128 v[220:223], v193 offset:36864
	ds_read_b128 v[224:227], v193 offset:37888
	ds_read_b128 v[228:231], v193 offset:38912
	ds_read_b128 v[232:235], v193 offset:39936
	global_load_lds_dwordx4 v[238:239], off
	v_lshl_add_u64 v[238:239], s[30:31], 0, v[164:165]
	s_mov_b32 m0, s43
	s_nop 0
	global_load_lds_dwordx4 v[238:239], off
	s_waitcnt vmcnt(8)
	s_waitcnt lgkmcnt(0)
	s_barrier
	s_setprio 1
	s_waitcnt lgkmcnt(0)
	v_mfma_f32_16x16x32_bf16 v[142:145], v[64:67], v[172:175], v[142:145]
	v_mfma_f32_16x16x32_bf16 v[138:141], v[88:91], v[172:175], v[138:141]
	v_mfma_f32_16x16x32_bf16 v[124:127], v[64:67], v[198:201], v[124:127]
	v_mfma_f32_16x16x32_bf16 v[120:123], v[88:91], v[198:201], v[120:123]
	v_mfma_f32_16x16x32_bf16 v[108:111], v[64:67], v[220:223], v[108:111]
	v_mfma_f32_16x16x32_bf16 v[104:107], v[88:91], v[220:223], v[104:107]
	v_mfma_f32_16x16x32_bf16 v[84:87], v[64:67], v[228:231], v[84:87]
	v_mfma_f32_16x16x32_bf16 v[80:83], v[88:91], v[228:231], v[80:83]
	v_mfma_f32_16x16x32_bf16 v[142:145], v[76:79], v[194:197], v[142:145]
	v_mfma_f32_16x16x32_bf16 v[138:141], v[100:103], v[194:197], v[138:141]
	v_mfma_f32_16x16x32_bf16 v[124:127], v[76:79], v[216:219], v[124:127]
	v_mfma_f32_16x16x32_bf16 v[120:123], v[100:103], v[216:219], v[120:123]
	v_mfma_f32_16x16x32_bf16 v[108:111], v[76:79], v[224:227], v[108:111]
	v_mfma_f32_16x16x32_bf16 v[104:107], v[100:103], v[224:227], v[104:107]
	v_mfma_f32_16x16x32_bf16 v[84:87], v[76:79], v[232:235], v[84:87]
	v_mfma_f32_16x16x32_bf16 v[80:83], v[100:103], v[232:235], v[80:83]
	s_setprio 0
	s_setprio 1
	v_mfma_f32_16x16x32_bf16 v[132:135], v[146:149], v[172:175], v[132:135]
	v_mfma_f32_16x16x32_bf16 v[128:131], v[154:157], v[172:175], v[128:131]
	v_mfma_f32_16x16x32_bf16 v[116:119], v[146:149], v[198:201], v[116:119]
	v_mfma_f32_16x16x32_bf16 v[112:115], v[154:157], v[198:201], v[112:115]
	v_mfma_f32_16x16x32_bf16 v[96:99], v[146:149], v[220:223], v[96:99]
	v_mfma_f32_16x16x32_bf16 v[92:95], v[154:157], v[220:223], v[92:95]
	v_mfma_f32_16x16x32_bf16 v[72:75], v[146:149], v[228:231], v[72:75]
	v_mfma_f32_16x16x32_bf16 v[68:71], v[154:157], v[228:231], v[68:71]
	v_mfma_f32_16x16x32_bf16 v[132:135], v[150:153], v[194:197], v[132:135]
	v_mfma_f32_16x16x32_bf16 v[128:131], v[158:161], v[194:197], v[128:131]
	v_mfma_f32_16x16x32_bf16 v[116:119], v[150:153], v[216:219], v[116:119]
	v_mfma_f32_16x16x32_bf16 v[112:115], v[158:161], v[216:219], v[112:115]
	v_mfma_f32_16x16x32_bf16 v[96:99], v[150:153], v[224:227], v[96:99]
	v_mfma_f32_16x16x32_bf16 v[92:95], v[158:161], v[224:227], v[92:95]
	v_mfma_f32_16x16x32_bf16 v[72:75], v[150:153], v[232:235], v[72:75]
	v_mfma_f32_16x16x32_bf16 v[68:71], v[158:161], v[232:235], v[68:71]
	s_setprio 0
	s_barrier
; #define PG8_STAGE(bufoff, gbase, voff) do { _Pragma("unroll") for (int _i = 0; _i < 2; ++_i) \
;         __builtin_amdgcn_global_load_lds((const unsigned*)((const char*)(gbase) + (voff)[_i]), (LAS unsigned*)(lds + (bufoff) + ldsw + _i * 8192), 16, 0, 0); } while (0)
; #define PG8_LDA(dst, b, h) do { _Pragma("unroll") for (int m = 0; m < 4; ++m) _Pragma("unroll") for (int k = 0; k < 2; ++k) dst[m][k] = *(const LAS bf16x8*)(lds + PG8_SA(b, h) + aoff + m * 2048 + k * 1024); } while (0)
; #define PG8_MMA(ai, bj, At, Bt) do { __builtin_amdgcn_s_setprio(1); _Pragma("unroll") for (int m = 0; m < 4; ++m) _Pragma("unroll") for (int n = 0; n < 2; ++n) _Pragma("unroll") for (int k = 0; k < 2; ++k) \
;         acc[ai][bj][m][n] = __builtin_amdgcn_mfma_f32_16x16x32_bf16(Bt[n][k], At[m][k], acc[ai][bj][m][n], 0, 0, 0); __builtin_amdgcn_s_setprio(0); } while (0)
; #define PG8_WAIT_V(n) asm volatile("s_waitcnt vmcnt(" #n ")" ::: "memory")
; #define PG8_WAIT_L(n) asm volatile("s_waitcnt lgkmcnt(" #n ")" ::: "memory")
; #define PG8_BAR __builtin_amdgcn_s_barrier()
; #define PG8_SCHED __builtin_amdgcn_sched_barrier(0)
; template <class Epi>
; __device__ __forceinline__ void gemm_phase(LAS unsigned char* lds, const Gemm g, const StaticOrder& S, const Epi& E, const int tid) {
;     ...
;             PG8_LDA(At, 1, 1); PG8_STAGE(PG8_SB(1, 0), b3, voffB); PG8_STAGE(PG8_SB(1, 1), b3 + hstepB, voffB); PG8_STAGE(PG8_SA(1, 0), a3, voffA);
;             PG8_WAIT_V(8); PG8_WAIT_L(0); PG8_BAR; PG8_MMA(1, 0, At, B0); PG8_MMA(1, 1, At, B1); PG8_BAR; PG8_SCHED;
;         }
;         if (wr == 0) PG8_BAR;
	s_add_i32 s30, s54, s39
	v_lshl_add_u64 v[176:177], v[176:177], 0, s[56:57]
	s_mov_b32 m0, s30
	ds_read_b128 v[172:175], v193 offset:49152
	ds_read_b128 v[194:197], v193 offset:50176
	ds_read_b128 v[198:201], v193 offset:51200
	ds_read_b128 v[216:219], v193 offset:52224
	ds_read_b128 v[220:223], v193 offset:53248
	ds_read_b128 v[224:227], v193 offset:54272
	ds_read_b128 v[228:231], v193 offset:55296
	ds_read_b128 v[232:235], v193 offset:56320
	global_load_lds_dwordx4 v[176:177], off
	s_add_i32 m0, s30, 0x2000
	s_add_u32 s28, s28, 0x80080
	v_lshl_add_u64 v[176:177], v[190:191], 0, s[56:57]
	s_addc_u32 s29, s29, 0
	s_add_i32 s30, s55, s39
	global_load_lds_dwordx4 v[176:177], off
	v_lshl_add_u64 v[176:177], s[28:29], 0, v[136:137]
	s_mov_b32 m0, s30
	s_nop 0
	global_load_lds_dwordx4 v[176:177], off
	v_lshl_add_u64 v[176:177], s[28:29], 0, v[162:163]
	s_add_i32 m0, s30, 0x2000
	s_nop 0
	global_load_lds_dwordx4 v[176:177], off
	v_lshl_add_u64 v[176:177], v[202:203], 0, s[56:57]
	s_mov_b32 m0, s44
	s_nop 0
	global_load_lds_dwordx4 v[176:177], off
	v_lshl_add_u64 v[176:177], v[236:237], 0, s[56:57]
	s_mov_b32 m0, s45
	s_nop 0
	global_load_lds_dwordx4 v[176:177], off
	s_waitcnt vmcnt(8)
	s_waitcnt lgkmcnt(0)
	s_barrier
	s_setprio 1
	s_waitcnt lgkmcnt(0)
	v_mfma_f32_16x16x32_bf16 v[60:63], v[64:67], v[172:175], v[60:63]
	v_mfma_f32_16x16x32_bf16 v[56:59], v[88:91], v[172:175], v[56:59]
	v_mfma_f32_16x16x32_bf16 v[44:47], v[64:67], v[198:201], v[44:47]
	v_mfma_f32_16x16x32_bf16 v[40:43], v[88:91], v[198:201], v[40:43]
	v_mfma_f32_16x16x32_bf16 v[28:31], v[64:67], v[220:223], v[28:31]
	v_mfma_f32_16x16x32_bf16 v[24:27], v[88:91], v[220:223], v[24:27]
	v_mfma_f32_16x16x32_bf16 v[12:15], v[64:67], v[228:231], v[12:15]
	v_mfma_f32_16x16x32_bf16 v[8:11], v[88:91], v[228:231], v[8:11]
	v_mfma_f32_16x16x32_bf16 v[60:63], v[76:79], v[194:197], v[60:63]
	v_mfma_f32_16x16x32_bf16 v[56:59], v[100:103], v[194:197], v[56:59]
	v_mfma_f32_16x16x32_bf16 v[44:47], v[76:79], v[216:219], v[44:47]
	v_mfma_f32_16x16x32_bf16 v[40:43], v[100:103], v[216:219], v[40:43]
	v_mfma_f32_16x16x32_bf16 v[28:31], v[76:79], v[224:227], v[28:31]
	v_mfma_f32_16x16x32_bf16 v[24:27], v[100:103], v[224:227], v[24:27]
	v_mfma_f32_16x16x32_bf16 v[12:15], v[76:79], v[232:235], v[12:15]
	v_mfma_f32_16x16x32_bf16 v[8:11], v[100:103], v[232:235], v[8:11]
	s_setprio 0
	s_setprio 1
	v_mfma_f32_16x16x32_bf16 v[52:55], v[146:149], v[172:175], v[52:55]
	v_mfma_f32_16x16x32_bf16 v[48:51], v[154:157], v[172:175], v[48:51]
	v_mfma_f32_16x16x32_bf16 v[36:39], v[146:149], v[198:201], v[36:39]
	v_mfma_f32_16x16x32_bf16 v[32:35], v[154:157], v[198:201], v[32:35]
	v_mfma_f32_16x16x32_bf16 v[20:23], v[146:149], v[220:223], v[20:23]
	v_mfma_f32_16x16x32_bf16 v[16:19], v[154:157], v[220:223], v[16:19]
	v_mfma_f32_16x16x32_bf16 v[4:7], v[146:149], v[228:231], v[4:7]
	v_mfma_f32_16x16x32_bf16 v[0:3], v[154:157], v[228:231], v[0:3]
	v_mfma_f32_16x16x32_bf16 v[52:55], v[150:153], v[194:197], v[52:55]
	v_mfma_f32_16x16x32_bf16 v[48:51], v[158:161], v[194:197], v[48:51]
	v_mfma_f32_16x16x32_bf16 v[36:39], v[150:153], v[216:219], v[36:39]
	v_mfma_f32_16x16x32_bf16 v[32:35], v[158:161], v[216:219], v[32:35]
	v_mfma_f32_16x16x32_bf16 v[20:23], v[150:153], v[224:227], v[20:23]
	v_mfma_f32_16x16x32_bf16 v[16:19], v[158:161], v[224:227], v[16:19]
	v_mfma_f32_16x16x32_bf16 v[4:7], v[150:153], v[232:235], v[4:7]
	v_mfma_f32_16x16x32_bf16 v[0:3], v[158:161], v[232:235], v[0:3]
	s_setprio 0
	s_barrier
	s_add_i32 s53, s53, 2
	s_add_u32 s6, s6, 0x100
	s_addc_u32 s7, s7, 0
	s_add_u32 s51, s51, 0x100
	s_addc_u32 s52, s52, 0
	s_cmp_gt_u32 s53, 13
	s_cbranch_scc0 .LBB0_35
	s_and_b64 vcc, exec, s[12:13]
	s_cbranch_vccz .LBB0_38
	s_barrier

; #define PG8_BAR __builtin_amdgcn_s_barrier()
; template <class Epi>
; __device__ __forceinline__ void gemm_phase(LAS unsigned char* lds, const Gemm g, const StaticOrder& S, const Epi& E, const int tid) {
;     ...
;         if (!has_next) break;
; #pragma unroll
;         for (int a = 0; a < 2; ++a)
; #pragma unroll
;             for (int b = 0; b < 2; ++b)
; #pragma unroll
;                 for (int m = 0; m < 4; ++m)
; #pragma unroll
;                     for (int n = 0; n < 2; ++n) acc[a][b][m][n] = (f32x4){0.f, 0.f, 0.f, 0.f};
;         cur = nxt; cA = nA; cB = nB; ++ui;
;         if (wr == 1) PG8_BAR;
.Le2_done:
	s_mov_b32 s98, 1
	s_andn2_b64 vcc, exec, s[4:5]
	s_mov_b64 s[4:5], -1
	s_cbranch_vccnz .LBB0_27
	s_andn2_b64 vcc, exec, s[8:9]
	s_cbranch_vccnz .LBB0_26
	s_barrier
	s_branch .LBB0_26

; #define PG8_STAGE(bufoff, gbase, voff) do { _Pragma("unroll") for (int _i = 0; _i < 2; ++_i) \
;         __builtin_amdgcn_global_load_lds((const unsigned*)((const char*)(gbase) + (voff)[_i]), (LAS unsigned*)(lds + (bufoff) + ldsw + _i * 8192), 16, 0, 0); } while (0)
; #define PG8_BAR __builtin_amdgcn_s_barrier()
; template <class Epi>
; __device__ __forceinline__ void gemm_phase(LAS unsigned char* lds, const Gemm g, const StaticOrder& S, const Epi& E, const int tid) {
;     const int wid = __builtin_amdgcn_readfirstlane(tid >> 6), lane = tid & 63, wr = wid >> 2, wc = wid & 3, fr = lane & 15, fq = lane >> 4;
;     const int K = g.K, nt = K / BK;
;     unsigned voffA[2], voffB[2];
; #pragma unroll
;     for (int i = 0; i < 2; ++i) { int R, C; stage_rc(tid * 16 + i * 8192, R, C); const int Rb = Epi::PERM ? ((R & ~31) + perm32(R & 31)) : R;
;         voffA[i] = (unsigned)(R * g.lda + C) * 2u; voffB[i] = (unsigned)(Rb * g.ldb + C) * 2u; }
;     const size_t kstep = (size_t)(BK * 2);
;     const size_t hstepA = (size_t)HALF * g.lda * 2, hstepB = (size_t)HALF * g.ldb * 2;
;     const size_t tstepA = 2 * hstepA, tstepB = 2 * hstepB;
;     const unsigned ldsw = (unsigned)wid * 1024u;
;     const int aoff = lds_byte(wr * 64 + fr, fq * 8), boff = lds_byte(wc * 32 + fr, fq * 8);
;     ...
;     Unit cur, nxt; int ui = 0;
;     if (!S.next(0, cur)) return;
;     f32x4 acc[2][2][4][2];
; #pragma unroll
;     for (int a = 0; a < 2; ++a)
; #pragma unroll
;         for (int b = 0; b < 2; ++b)
; #pragma unroll
;             for (int m = 0; m < 4; ++m)
; #pragma unroll
;                 for (int n = 0; n < 2; ++n) acc[a][b][m][n] = (f32x4){0.f, 0.f, 0.f, 0.f};
;     bf16x8 At[4][2], B0[2][2], B1[2][2];
;     const char* cA = (const char*)g.A + (size_t)cur.pm * tstepA + (size_t)cur.half * K * 2; const char* cB = (const char*)g.Bt + (size_t)cur.pn * tstepB + (size_t)cur.half * K * 2;
;     PG8_STAGE(PG8_SB(0, 0), cB, voffB); PG8_STAGE(PG8_SB(0, 1), cB + hstepB, voffB); PG8_STAGE(PG8_SA(0, 0), cA, voffA); PG8_STAGE(PG8_SA(0, 1), cA + hstepA, voffA);
;     if (wr == 1) PG8_BAR;
.LBB0_476:
	s_and_b64 vcc, exec, s[4:5]
	s_cbranch_vccnz .LBB0_616
	s_mov_b32 s98, 0
	v_ashrrev_i32_e32 v1, 31, v188
	v_lshrrev_b32_e32 v1, 26, v1
	v_add_u32_e32 v1, v188, v1
	v_ashrrev_i32_e32 v8, 6, v1
	v_bfe_i32 v1, v188, 27, 1
	v_lshlrev_b32_e32 v0, 4, v188
	v_lshrrev_b32_e32 v1, 22, v1
	v_add_u32_e32 v1, v0, v1
	v_and_b32_e32 v1, 0xfffffc00, v1
	v_sub_u32_e32 v1, v0, v1
	v_lshrrev_b32_e32 v2, 4, v1
	v_bitop3_b32 v1, v2, v1, 32 bitop3:0x6c
	v_ashrrev_i32_e32 v3, 31, v1
	v_lshrrev_b32_e32 v3, 26, v3
	v_add_u32_e32 v3, v1, v3
	v_lshlrev_b32_e32 v2, 3, v8
	v_ashrrev_i32_e32 v9, 6, v3
	v_and_b32_e32 v3, 0xc0, v3
	v_and_b32_e32 v2, -16, v2
	v_sub_u32_e32 v1, v1, v3
	v_readlane_b32 s0, v248, 24
	v_add_u32_e32 v2, v9, v2
	v_ashrrev_i16_sdwa v1, v208, sext(v1) dst_sel:DWORD dst_unused:UNUSED_PAD src0_sel:DWORD src1_sel:BYTE_0
	v_lshlrev_b32_e32 v4, 5, v8
	v_bfe_i32 v10, v1, 0, 16
	v_lshlrev_b32_e32 v1, 1, v2
	v_lshrrev_b32_e32 v3, 2, v2
	v_and_b32_e32 v5, 3, v9
	s_mov_b32 s0, 0xfffe0
	v_and_b32_e32 v4, 32, v4
	v_and_b32_e32 v1, 24, v1
	v_and_b32_e32 v3, 4, v3
	v_and_or_b32 v5, v2, s0, v5
	v_or3_b32 v1, v5, v3, v1
	v_add_lshl_u32 v3, v4, v10, 1
	v_add_u32_e32 v0, 0x2000, v0
	v_lshl_add_u32 v136, v1, 12, v3
	v_ashrrev_i32_e32 v1, 31, v0
	v_lshrrev_b32_e32 v1, 22, v1
	v_add_u32_e32 v1, v0, v1
	v_ashrrev_i32_e32 v11, 10, v1
	v_mul_i32_i24_e32 v1, 0x400, v11
	v_sub_u32_e32 v0, v0, v1
	v_lshrrev_b32_e32 v1, 4, v0
	v_bitop3_b32 v0, v1, v0, 32 bitop3:0x6c
	v_lshl_add_u32 v138, v2, 12, v3
	v_ashrrev_i32_e32 v2, 31, v0
	v_lshrrev_b32_e32 v2, 26, v2
	s_add_u32 s52, s8, 0x4100000
	v_add_u32_e32 v2, v0, v2
	s_addc_u32 s53, s9, 0
	s_ashr_i32 s21, s20, 6
	v_lshlrev_b32_e32 v1, 3, v11
	v_ashrrev_i32_e32 v12, 6, v2
	v_and_b32_e32 v2, 0xc0, v2
	s_ashr_i32 s3, s2, 31
	s_ashr_i32 s45, s44, 31
	v_and_b32_e32 v1, -16, v1
	v_sub_u32_e32 v0, v0, v2
	s_ashr_i32 s24, s20, 8
	s_lshl_b32 s54, s21, 10
	s_lshl_b64 s[4:5], s[2:3], 20
	s_lshl_b64 s[6:7], s[44:45], 20
	v_add_u32_e32 v1, v12, v1
	v_ashrrev_i16_sdwa v0, v208, sext(v0) dst_sel:DWORD dst_unused:UNUSED_PAD src0_sel:DWORD src1_sel:BYTE_0
	s_add_u32 s46, s8, s6
	v_lshlrev_b32_e32 v3, 5, v11
	v_bfe_i32 v13, v0, 0, 16
	v_lshlrev_b32_e32 v0, 1, v1
	v_lshrrev_b32_e32 v2, 2, v1
	v_and_b32_e32 v4, 3, v12
	s_addc_u32 s47, s9, s7
	s_add_i32 s55, s54, 0
	v_and_b32_e32 v3, 32, v3
	v_and_b32_e32 v0, 24, v0
	v_and_b32_e32 v2, 4, v2
	v_and_or_b32 v4, v1, s0, v4
	s_add_i32 m0, s55, 0x10000
	v_or3_b32 v0, v4, v2, v0
	v_add_lshl_u32 v2, v3, v13, 1
	global_load_lds_dwordx4 v136, s[46:47]
	s_add_i32 m0, s55, 0x12000
	v_lshl_add_u32 v142, v0, 12, v2
	s_add_u32 s6, s46, 0x80000
	global_load_lds_dwordx4 v142, s[46:47]
	s_addc_u32 s7, s47, 0
	s_add_i32 m0, s55, 0x14000
	v_lshl_add_u32 v140, v1, 12, v2
	global_load_lds_dwordx4 v136, s[6:7]
	s_add_i32 m0, s55, 0x16000
	s_add_u32 s36, s52, s4
	s_addc_u32 s37, s53, s5
	s_add_i32 s68, s55, 0x2000
	global_load_lds_dwordx4 v142, s[6:7]
	s_mov_b32 m0, s55
	s_add_u32 s4, s36, 0x80000
	global_load_lds_dwordx4 v138, s[36:37]
	s_mov_b32 m0, s68
	s_addc_u32 s5, s37, 0
	s_add_i32 s69, s55, 0x4000
	global_load_lds_dwordx4 v140, s[36:37]
	s_mov_b32 m0, s69
	s_add_i32 s70, s55, 0x6000
	global_load_lds_dwordx4 v138, s[4:5]
	s_mov_b32 m0, s70
	v_readlane_b32 s8, v248, 4
	global_load_lds_dwordx4 v140, s[4:5]
	v_readlane_b32 s9, v248, 5
	s_load_dwordx4 s[4:7], s[8:9], 0x68
	v_mov_b32_e32 v143, v137
	v_mov_b32_e32 v139, v137
	v_mov_b32_e32 v141, v137
	s_cmp_eq_u32 s24, 1
	v_lshl_add_u64 v[6:7], s[46:47], 0, v[136:137]
	v_lshl_add_u64 v[4:5], s[46:47], 0, v[142:143]
	v_lshl_add_u64 v[0:1], s[36:37], 0, v[138:139]
	s_cselect_b64 s[8:9], -1, 0
	s_cmp_lg_u32 s24, 1
	v_lshl_add_u64 v[2:3], s[36:37], 0, v[140:141]
	s_cbranch_scc1 .LBB0_479
	s_barrier

; #define PG8_STAGE(bufoff, gbase, voff) do { _Pragma("unroll") for (int _i = 0; _i < 2; ++_i) \
;         __builtin_amdgcn_global_load_lds((const unsigned*)((const char*)(gbase) + (voff)[_i]), (LAS unsigned*)(lds + (bufoff) + ldsw + _i * 8192), 16, 0, 0); } while (0)
; #define PG8_LDA(dst, b, h) do { _Pragma("unroll") for (int m = 0; m < 4; ++m) _Pragma("unroll") for (int k = 0; k < 2; ++k) dst[m][k] = *(const LAS bf16x8*)(lds + PG8_SA(b, h) + aoff + m * 2048 + k * 1024); } while (0)
; #define PG8_LDB(dst, b, h) do { _Pragma("unroll") for (int n = 0; n < 2; ++n) _Pragma("unroll") for (int k = 0; k < 2; ++k) dst[n][k] = *(const LAS bf16x8*)(lds + PG8_SB(b, h) + boff + n * 2048 + k * 1024); } while (0)
; #define PG8_MMA(ai, bj, At, Bt) do { __builtin_amdgcn_s_setprio(1); _Pragma("unroll") for (int m = 0; m < 4; ++m) _Pragma("unroll") for (int n = 0; n < 2; ++n) _Pragma("unroll") for (int k = 0; k < 2; ++k) \
;         acc[ai][bj][m][n] = __builtin_amdgcn_mfma_f32_16x16x32_bf16(Bt[n][k], At[m][k], acc[ai][bj][m][n], 0, 0, 0); __builtin_amdgcn_s_setprio(0); } while (0)
; #define PG8_WAIT_V(n) asm volatile("s_waitcnt vmcnt(" #n ")" ::: "memory")
; #define PG8_WAIT_L(n) asm volatile("s_waitcnt lgkmcnt(" #n ")" ::: "memory")
; #define PG8_BAR __builtin_amdgcn_s_barrier()
; #define PG8_SCHED __builtin_amdgcn_sched_barrier(0)
; template <class Epi>
; __device__ __forceinline__ void gemm_phase(LAS unsigned char* lds, const Gemm g, const StaticOrder& S, const Epi& E, const int tid) {
;     ...
;         for (int t = 0; t < nt; t += 2) {
;             const bool last = (t == nt - 2);
;             const char* a1 = cA + (size_t)(t + 1) * kstep;
;             const char* a2 = last ? nA : cA + (size_t)(t + 2) * kstep; const char* b2 = last ? nB : cB + (size_t)(t + 2) * kstep;
;             const char* a3 = a2 + kstep; const char* b3 = b2 + kstep;
;             PG8_LDB(B0, 0, 0); PG8_LDB(B1, 0, 1); PG8_SCHED; PG8_LDA(At, 0, 0); PG8_STAGE(PG8_SA(1, 1), a1 + hstepA, voffA);
;             PG8_WAIT_V(8); PG8_WAIT_L(0); PG8_BAR; PG8_MMA(0, 0, At, B0); PG8_MMA(0, 1, At, B1); PG8_BAR; PG8_SCHED;
.LBB0_489:
	s_add_u32 s46, s36, 0xfff80080
	s_addc_u32 s47, s37, -1
	s_add_i32 s76, 0, 0x10000
	s_cmp_eq_u32 s51, 28
	s_cselect_b32 s49, s3, s47
	s_cselect_b32 s48, s29, s46
	v_add_u32_e32 v154, s76, v157
	s_cselect_b32 s47, s27, s50
	s_cselect_b32 s46, s39, s45
	s_add_i32 s78, 0, 0x14000
	ds_read_b128 v[128:131], v154
	ds_read_b128 v[132:135], v154 offset:1024
	ds_read_b128 v[150:153], v154 offset:2048
	ds_read_b128 v[160:163], v154 offset:3072
	v_add_u32_e32 v154, s78, v157
	ds_read_b128 v[164:167], v154
	ds_read_b128 v[168:171], v154 offset:1024
	ds_read_b128 v[172:175], v154 offset:2048
	ds_read_b128 v[190:193], v154 offset:3072
	v_lshl_add_u64 v[154:155], s[36:37], 0, v[146:147]
	s_add_i32 m0, s55, 0xc000
	ds_read_b128 v[194:197], v159
	ds_read_b128 v[198:201], v159 offset:1024
	ds_read_b128 v[216:219], v159 offset:2048
	ds_read_b128 v[220:223], v159 offset:3072
	ds_read_b128 v[224:227], v159 offset:4096
	ds_read_b128 v[228:231], v159 offset:5120
	ds_read_b128 v[232:235], v159 offset:6144
	ds_read_b128 v[236:239], v159 offset:7168
	global_load_lds_dwordx4 v[154:155], off
	v_lshl_add_u64 v[154:155], s[36:37], 0, v[148:149]
	s_add_i32 m0, s55, 0xe000
	s_nop 0
	global_load_lds_dwordx4 v[154:155], off
	s_cmp_lg_u32 s98, 0
	s_cbranch_scc1 .Ltb_g10r
	s_waitcnt vmcnt(8)
	s_branch .Ltb_g10d

; #define PG8_STAGE(bufoff, gbase, voff) do { _Pragma("unroll") for (int _i = 0; _i < 2; ++_i) \
;         __builtin_amdgcn_global_load_lds((const unsigned*)((const char*)(gbase) + (voff)[_i]), (LAS unsigned*)(lds + (bufoff) + ldsw + _i * 8192), 16, 0, 0); } while (0)
; #define PG8_LDA(dst, b, h) do { _Pragma("unroll") for (int m = 0; m < 4; ++m) _Pragma("unroll") for (int k = 0; k < 2; ++k) dst[m][k] = *(const LAS bf16x8*)(lds + PG8_SA(b, h) + aoff + m * 2048 + k * 1024); } while (0)
; #define PG8_MMA(ai, bj, At, Bt) do { __builtin_amdgcn_s_setprio(1); _Pragma("unroll") for (int m = 0; m < 4; ++m) _Pragma("unroll") for (int n = 0; n < 2; ++n) _Pragma("unroll") for (int k = 0; k < 2; ++k) \
;         acc[ai][bj][m][n] = __builtin_amdgcn_mfma_f32_16x16x32_bf16(Bt[n][k], At[m][k], acc[ai][bj][m][n], 0, 0, 0); __builtin_amdgcn_s_setprio(0); } while (0)
; #define PG8_WAIT_V(n) asm volatile("s_waitcnt vmcnt(" #n ")" ::: "memory")
; #define PG8_WAIT_L(n) asm volatile("s_waitcnt lgkmcnt(" #n ")" ::: "memory")
; #define PG8_BAR __builtin_amdgcn_s_barrier()
; #define PG8_SCHED __builtin_amdgcn_sched_barrier(0)
; template <class Epi>
; __device__ __forceinline__ void gemm_phase(LAS unsigned char* lds, const Gemm g, const StaticOrder& S, const Epi& E, const int tid) {
;     ...
;             PG8_WAIT_V(8); PG8_WAIT_L(0); PG8_BAR; PG8_MMA(0, 0, At, B0); PG8_MMA(0, 1, At, B1); PG8_BAR; PG8_SCHED;
;             PG8_LDA(At, 0, 1); PG8_STAGE(PG8_SB(0, 0), b2, voffB); PG8_STAGE(PG8_SB(0, 1), b2 + hstepB, voffB); PG8_STAGE(PG8_SA(0, 0), a2, voffA);
;             PG8_WAIT_V(8); PG8_WAIT_L(0); PG8_BAR; PG8_MMA(1, 0, At, B0); PG8_MMA(1, 1, At, B1); PG8_BAR; PG8_SCHED;
.Ltb_g10d:
	s_waitcnt lgkmcnt(0)
	s_barrier
	s_setprio 1
	s_waitcnt lgkmcnt(0)
	v_mfma_f32_16x16x32_bf16 v[56:59], v[128:131], v[194:197], v[56:59]
	v_mfma_f32_16x16x32_bf16 v[60:63], v[150:153], v[194:197], v[60:63]
	v_mfma_f32_16x16x32_bf16 v[48:51], v[128:131], v[216:219], v[48:51]
	v_mfma_f32_16x16x32_bf16 v[52:55], v[150:153], v[216:219], v[52:55]
	v_mfma_f32_16x16x32_bf16 v[40:43], v[128:131], v[224:227], v[40:43]
	v_mfma_f32_16x16x32_bf16 v[44:47], v[150:153], v[224:227], v[44:47]
	v_mfma_f32_16x16x32_bf16 v[32:35], v[128:131], v[232:235], v[32:35]
	v_mfma_f32_16x16x32_bf16 v[36:39], v[150:153], v[232:235], v[36:39]
	v_mfma_f32_16x16x32_bf16 v[56:59], v[132:135], v[198:201], v[56:59]
	v_mfma_f32_16x16x32_bf16 v[60:63], v[160:163], v[198:201], v[60:63]
	v_mfma_f32_16x16x32_bf16 v[48:51], v[132:135], v[220:223], v[48:51]
	v_mfma_f32_16x16x32_bf16 v[52:55], v[160:163], v[220:223], v[52:55]
	v_mfma_f32_16x16x32_bf16 v[40:43], v[132:135], v[228:231], v[40:43]
	v_mfma_f32_16x16x32_bf16 v[44:47], v[160:163], v[228:231], v[44:47]
	v_mfma_f32_16x16x32_bf16 v[32:35], v[132:135], v[236:239], v[32:35]
	v_mfma_f32_16x16x32_bf16 v[36:39], v[160:163], v[236:239], v[36:39]
	s_setprio 0
	s_setprio 1
	v_mfma_f32_16x16x32_bf16 v[120:123], v[164:167], v[194:197], v[120:123]
	v_mfma_f32_16x16x32_bf16 v[124:127], v[172:175], v[194:197], v[124:127]
	v_mfma_f32_16x16x32_bf16 v[112:115], v[164:167], v[216:219], v[112:115]
	v_mfma_f32_16x16x32_bf16 v[116:119], v[172:175], v[216:219], v[116:119]
	v_mfma_f32_16x16x32_bf16 v[104:107], v[164:167], v[224:227], v[104:107]
	v_mfma_f32_16x16x32_bf16 v[108:111], v[172:175], v[224:227], v[108:111]
	v_mfma_f32_16x16x32_bf16 v[96:99], v[164:167], v[232:235], v[96:99]
	v_mfma_f32_16x16x32_bf16 v[100:103], v[172:175], v[232:235], v[100:103]
	v_mfma_f32_16x16x32_bf16 v[120:123], v[168:171], v[198:201], v[120:123]
	v_mfma_f32_16x16x32_bf16 v[124:127], v[190:193], v[198:201], v[124:127]
	v_mfma_f32_16x16x32_bf16 v[112:115], v[168:171], v[220:223], v[112:115]
	v_mfma_f32_16x16x32_bf16 v[116:119], v[190:193], v[220:223], v[116:119]
	v_mfma_f32_16x16x32_bf16 v[104:107], v[168:171], v[228:231], v[104:107]
	v_mfma_f32_16x16x32_bf16 v[108:111], v[190:193], v[228:231], v[108:111]
	v_mfma_f32_16x16x32_bf16 v[96:99], v[168:171], v[236:239], v[96:99]
	v_mfma_f32_16x16x32_bf16 v[100:103], v[190:193], v[236:239], v[100:103]
	s_setprio 0
	s_barrier
	s_add_i32 s76, s76, s54
	v_lshl_add_u64 v[154:155], s[46:47], 0, v[136:137]
	s_mov_b32 m0, s76
	ds_read_b128 v[194:197], v159 offset:16384
	ds_read_b128 v[198:201], v159 offset:17408
	ds_read_b128 v[216:219], v159 offset:18432
	ds_read_b128 v[220:223], v159 offset:19456
	ds_read_b128 v[224:227], v159 offset:20480
	ds_read_b128 v[228:231], v159 offset:21504
	ds_read_b128 v[232:235], v159 offset:22528
	ds_read_b128 v[236:239], v159 offset:23552
	global_load_lds_dwordx4 v[154:155], off
	s_add_i32 m0, s76, 0x2000
	s_add_u32 s76, s46, 0x80000
	v_lshl_add_u64 v[176:177], s[46:47], 0, v[142:143]
	s_addc_u32 s77, s47, 0
	s_add_i32 s78, s78, s54
	global_load_lds_dwordx4 v[176:177], off
	v_lshl_add_u64 v[202:203], s[76:77], 0, v[136:137]
	s_mov_b32 m0, s78
	v_lshl_add_u64 v[240:241], s[48:49], 0, v[140:141]
	global_load_lds_dwordx4 v[202:203], off
	v_lshl_add_u64 v[202:203], s[76:77], 0, v[142:143]
	s_add_i32 m0, s78, 0x2000
	s_nop 0
	global_load_lds_dwordx4 v[202:203], off
	v_lshl_add_u64 v[202:203], s[48:49], 0, v[138:139]
	s_mov_b32 m0, s55
	s_nop 0
	global_load_lds_dwordx4 v[202:203], off
	s_mov_b32 m0, s68
	s_nop 0
	global_load_lds_dwordx4 v[240:241], off
	s_cmp_lg_u32 s98, 0
	s_cbranch_scc1 .Ltb_g11r
	s_waitcnt vmcnt(8)
	s_branch .Ltb_g11d

; #define PG8_STAGE(bufoff, gbase, voff) do { _Pragma("unroll") for (int _i = 0; _i < 2; ++_i) \
;         __builtin_amdgcn_global_load_lds((const unsigned*)((const char*)(gbase) + (voff)[_i]), (LAS unsigned*)(lds + (bufoff) + ldsw + _i * 8192), 16, 0, 0); } while (0)
; #define PG8_LDA(dst, b, h) do { _Pragma("unroll") for (int m = 0; m < 4; ++m) _Pragma("unroll") for (int k = 0; k < 2; ++k) dst[m][k] = *(const LAS bf16x8*)(lds + PG8_SA(b, h) + aoff + m * 2048 + k * 1024); } while (0)
; #define PG8_LDB(dst, b, h) do { _Pragma("unroll") for (int n = 0; n < 2; ++n) _Pragma("unroll") for (int k = 0; k < 2; ++k) dst[n][k] = *(const LAS bf16x8*)(lds + PG8_SB(b, h) + boff + n * 2048 + k * 1024); } while (0)
; #define PG8_MMA(ai, bj, At, Bt) do { __builtin_amdgcn_s_setprio(1); _Pragma("unroll") for (int m = 0; m < 4; ++m) _Pragma("unroll") for (int n = 0; n < 2; ++n) _Pragma("unroll") for (int k = 0; k < 2; ++k) \
;         acc[ai][bj][m][n] = __builtin_amdgcn_mfma_f32_16x16x32_bf16(Bt[n][k], At[m][k], acc[ai][bj][m][n], 0, 0, 0); __builtin_amdgcn_s_setprio(0); } while (0)
; #define PG8_WAIT_V(n) asm volatile("s_waitcnt vmcnt(" #n ")" ::: "memory")
; #define PG8_WAIT_L(n) asm volatile("s_waitcnt lgkmcnt(" #n ")" ::: "memory")
; #define PG8_BAR __builtin_amdgcn_s_barrier()
; #define PG8_SCHED __builtin_amdgcn_sched_barrier(0)
; template <class Epi>
; __device__ __forceinline__ void gemm_phase(LAS unsigned char* lds, const Gemm g, const StaticOrder& S, const Epi& E, const int tid) {
;     ...
;             PG8_WAIT_V(8); PG8_WAIT_L(0); PG8_BAR; PG8_MMA(1, 0, At, B0); PG8_MMA(1, 1, At, B1); PG8_BAR; PG8_SCHED;
;             PG8_LDB(B0, 1, 0); PG8_LDB(B1, 1, 1); PG8_SCHED; PG8_LDA(At, 1, 0); PG8_STAGE(PG8_SA(0, 1), a2 + hstepA, voffA);
;             PG8_WAIT_V(8); PG8_WAIT_L(0); PG8_BAR; PG8_MMA(0, 0, At, B0); PG8_MMA(0, 1, At, B1); PG8_BAR; PG8_SCHED;
.Ltb_g11d:
	s_mov_b32 s98, 0
	s_waitcnt lgkmcnt(0)
	s_barrier
	s_setprio 1
	s_waitcnt lgkmcnt(0)
	v_mfma_f32_16x16x32_bf16 v[24:27], v[128:131], v[194:197], v[24:27]
	v_mfma_f32_16x16x32_bf16 v[28:31], v[150:153], v[194:197], v[28:31]
	v_mfma_f32_16x16x32_bf16 v[16:19], v[128:131], v[216:219], v[16:19]
	v_mfma_f32_16x16x32_bf16 v[20:23], v[150:153], v[216:219], v[20:23]
	v_mfma_f32_16x16x32_bf16 v[8:11], v[128:131], v[224:227], v[8:11]
	v_mfma_f32_16x16x32_bf16 v[12:15], v[150:153], v[224:227], v[12:15]
	v_mfma_f32_16x16x32_bf16 v[0:3], v[128:131], v[232:235], v[0:3]
	v_mfma_f32_16x16x32_bf16 v[4:7], v[150:153], v[232:235], v[4:7]
	v_mfma_f32_16x16x32_bf16 v[24:27], v[132:135], v[198:201], v[24:27]
	v_mfma_f32_16x16x32_bf16 v[28:31], v[160:163], v[198:201], v[28:31]
	v_mfma_f32_16x16x32_bf16 v[16:19], v[132:135], v[220:223], v[16:19]
	v_mfma_f32_16x16x32_bf16 v[20:23], v[160:163], v[220:223], v[20:23]
	v_mfma_f32_16x16x32_bf16 v[8:11], v[132:135], v[228:231], v[8:11]
	v_mfma_f32_16x16x32_bf16 v[12:15], v[160:163], v[228:231], v[12:15]
	v_mfma_f32_16x16x32_bf16 v[0:3], v[132:135], v[236:239], v[0:3]
	v_mfma_f32_16x16x32_bf16 v[4:7], v[160:163], v[236:239], v[4:7]
	s_setprio 0
	s_setprio 1
	v_mfma_f32_16x16x32_bf16 v[88:91], v[164:167], v[194:197], v[88:91]
	v_mfma_f32_16x16x32_bf16 v[92:95], v[172:175], v[194:197], v[92:95]
	v_mfma_f32_16x16x32_bf16 v[80:83], v[164:167], v[216:219], v[80:83]
	v_mfma_f32_16x16x32_bf16 v[84:87], v[172:175], v[216:219], v[84:87]
	v_mfma_f32_16x16x32_bf16 v[72:75], v[164:167], v[224:227], v[72:75]
	v_mfma_f32_16x16x32_bf16 v[76:79], v[172:175], v[224:227], v[76:79]
	v_mfma_f32_16x16x32_bf16 v[64:67], v[164:167], v[232:235], v[64:67]
	v_mfma_f32_16x16x32_bf16 v[68:71], v[172:175], v[232:235], v[68:71]
	v_mfma_f32_16x16x32_bf16 v[88:91], v[168:171], v[198:201], v[88:91]
	v_mfma_f32_16x16x32_bf16 v[92:95], v[190:193], v[198:201], v[92:95]
	v_mfma_f32_16x16x32_bf16 v[80:83], v[168:171], v[220:223], v[80:83]
	v_mfma_f32_16x16x32_bf16 v[84:87], v[190:193], v[220:223], v[84:87]
	v_mfma_f32_16x16x32_bf16 v[72:75], v[168:171], v[228:231], v[72:75]
	v_mfma_f32_16x16x32_bf16 v[76:79], v[190:193], v[228:231], v[76:79]
	v_mfma_f32_16x16x32_bf16 v[64:67], v[168:171], v[236:239], v[64:67]
	v_mfma_f32_16x16x32_bf16 v[68:71], v[190:193], v[236:239], v[68:71]
	s_setprio 0
	s_barrier
	s_add_i32 s76, 0, 0x18000
	s_add_i32 s77, 0, 0x1c000
	v_add_u32_e32 v160, s76, v157
	v_add_u32_e32 v187, s77, v157
	ds_read_b128 v[128:131], v160
	ds_read_b128 v[132:135], v160 offset:1024
	ds_read_b128 v[150:153], v160 offset:2048
	ds_read_b128 v[160:163], v160 offset:3072
	ds_read_b128 v[164:167], v187
	ds_read_b128 v[168:171], v187 offset:1024
	ds_read_b128 v[172:175], v187 offset:2048
	ds_read_b128 v[190:193], v187 offset:3072
	s_add_u32 s48, s48, 0x80000
	s_addc_u32 s49, s49, 0
	s_mov_b32 m0, s69
	v_lshl_add_u64 v[242:243], s[48:49], 0, v[138:139]
	ds_read_b128 v[194:197], v159 offset:32768
	ds_read_b128 v[198:201], v159 offset:33792
	ds_read_b128 v[216:219], v159 offset:34816
	ds_read_b128 v[220:223], v159 offset:35840
	ds_read_b128 v[224:227], v159 offset:36864
	ds_read_b128 v[228:231], v159 offset:37888
	ds_read_b128 v[232:235], v159 offset:38912
	ds_read_b128 v[236:239], v159 offset:39936
	global_load_lds_dwordx4 v[242:243], off
	v_lshl_add_u64 v[242:243], s[48:49], 0, v[140:141]
	s_mov_b32 m0, s70
	s_nop 0
	global_load_lds_dwordx4 v[242:243], off
	s_waitcnt vmcnt(8)
	s_waitcnt lgkmcnt(0)
	s_barrier
	s_setprio 1
	s_waitcnt lgkmcnt(0)
	v_mfma_f32_16x16x32_bf16 v[56:59], v[128:131], v[194:197], v[56:59]
	v_mfma_f32_16x16x32_bf16 v[60:63], v[150:153], v[194:197], v[60:63]
	v_mfma_f32_16x16x32_bf16 v[48:51], v[128:131], v[216:219], v[48:51]
	v_mfma_f32_16x16x32_bf16 v[52:55], v[150:153], v[216:219], v[52:55]
	v_mfma_f32_16x16x32_bf16 v[40:43], v[128:131], v[224:227], v[40:43]
	v_mfma_f32_16x16x32_bf16 v[44:47], v[150:153], v[224:227], v[44:47]
	v_mfma_f32_16x16x32_bf16 v[32:35], v[128:131], v[232:235], v[32:35]
	v_mfma_f32_16x16x32_bf16 v[36:39], v[150:153], v[232:235], v[36:39]
	v_mfma_f32_16x16x32_bf16 v[56:59], v[132:135], v[198:201], v[56:59]
	v_mfma_f32_16x16x32_bf16 v[60:63], v[160:163], v[198:201], v[60:63]
	v_mfma_f32_16x16x32_bf16 v[48:51], v[132:135], v[220:223], v[48:51]
	v_mfma_f32_16x16x32_bf16 v[52:55], v[160:163], v[220:223], v[52:55]
	v_mfma_f32_16x16x32_bf16 v[40:43], v[132:135], v[228:231], v[40:43]
	v_mfma_f32_16x16x32_bf16 v[44:47], v[160:163], v[228:231], v[44:47]
	v_mfma_f32_16x16x32_bf16 v[32:35], v[132:135], v[236:239], v[32:35]
	v_mfma_f32_16x16x32_bf16 v[36:39], v[160:163], v[236:239], v[36:39]
	s_setprio 0
	s_setprio 1
	v_mfma_f32_16x16x32_bf16 v[120:123], v[164:167], v[194:197], v[120:123]
	v_mfma_f32_16x16x32_bf16 v[124:127], v[172:175], v[194:197], v[124:127]
	v_mfma_f32_16x16x32_bf16 v[112:115], v[164:167], v[216:219], v[112:115]
	v_mfma_f32_16x16x32_bf16 v[116:119], v[172:175], v[216:219], v[116:119]
	v_mfma_f32_16x16x32_bf16 v[104:107], v[164:167], v[224:227], v[104:107]
	v_mfma_f32_16x16x32_bf16 v[108:111], v[172:175], v[224:227], v[108:111]
	v_mfma_f32_16x16x32_bf16 v[96:99], v[164:167], v[232:235], v[96:99]
	v_mfma_f32_16x16x32_bf16 v[100:103], v[172:175], v[232:235], v[100:103]
	v_mfma_f32_16x16x32_bf16 v[120:123], v[168:171], v[198:201], v[120:123]
	v_mfma_f32_16x16x32_bf16 v[124:127], v[190:193], v[198:201], v[124:127]
	v_mfma_f32_16x16x32_bf16 v[112:115], v[168:171], v[220:223], v[112:115]
	v_mfma_f32_16x16x32_bf16 v[116:119], v[190:193], v[220:223], v[116:119]
	v_mfma_f32_16x16x32_bf16 v[104:107], v[168:171], v[228:231], v[104:107]
	v_mfma_f32_16x16x32_bf16 v[108:111], v[190:193], v[228:231], v[108:111]
	v_mfma_f32_16x16x32_bf16 v[96:99], v[168:171], v[236:239], v[96:99]
	v_mfma_f32_16x16x32_bf16 v[100:103], v[190:193], v[236:239], v[100:103]
	s_setprio 0
	s_barrier
; #define PG8_STAGE(bufoff, gbase, voff) do { _Pragma("unroll") for (int _i = 0; _i < 2; ++_i) \
;         __builtin_amdgcn_global_load_lds((const unsigned*)((const char*)(gbase) + (voff)[_i]), (LAS unsigned*)(lds + (bufoff) + ldsw + _i * 8192), 16, 0, 0); } while (0)
; #define PG8_LDA(dst, b, h) do { _Pragma("unroll") for (int m = 0; m < 4; ++m) _Pragma("unroll") for (int k = 0; k < 2; ++k) dst[m][k] = *(const LAS bf16x8*)(lds + PG8_SA(b, h) + aoff + m * 2048 + k * 1024); } while (0)
; #define PG8_MMA(ai, bj, At, Bt) do { __builtin_amdgcn_s_setprio(1); _Pragma("unroll") for (int m = 0; m < 4; ++m) _Pragma("unroll") for (int n = 0; n < 2; ++n) _Pragma("unroll") for (int k = 0; k < 2; ++k) \
;         acc[ai][bj][m][n] = __builtin_amdgcn_mfma_f32_16x16x32_bf16(Bt[n][k], At[m][k], acc[ai][bj][m][n], 0, 0, 0); __builtin_amdgcn_s_setprio(0); } while (0)
; #define PG8_WAIT_V(n) asm volatile("s_waitcnt vmcnt(" #n ")" ::: "memory")
; #define PG8_WAIT_L(n) asm volatile("s_waitcnt lgkmcnt(" #n ")" ::: "memory")
; #define PG8_BAR __builtin_amdgcn_s_barrier()
; #define PG8_SCHED __builtin_amdgcn_sched_barrier(0)
; template <class Epi>
; __device__ __forceinline__ void gemm_phase(LAS unsigned char* lds, const Gemm g, const StaticOrder& S, const Epi& E, const int tid) {
;     ...
;             PG8_LDA(At, 1, 1); PG8_STAGE(PG8_SB(1, 0), b3, voffB); PG8_STAGE(PG8_SB(1, 1), b3 + hstepB, voffB); PG8_STAGE(PG8_SA(1, 0), a3, voffA);
;             PG8_WAIT_V(8); PG8_WAIT_L(0); PG8_BAR; PG8_MMA(1, 0, At, B0); PG8_MMA(1, 1, At, B1); PG8_BAR; PG8_SCHED;
;         }
;         if (wr == 0) PG8_BAR;
	s_add_i32 s48, s76, s54
	v_lshl_add_u64 v[154:155], v[154:155], 0, s[56:57]
	s_mov_b32 m0, s48
	ds_read_b128 v[194:197], v159 offset:49152
	ds_read_b128 v[198:201], v159 offset:50176
	ds_read_b128 v[216:219], v159 offset:51200
	ds_read_b128 v[220:223], v159 offset:52224
	ds_read_b128 v[224:227], v159 offset:53248
	ds_read_b128 v[228:231], v159 offset:54272
	ds_read_b128 v[232:235], v159 offset:55296
	ds_read_b128 v[236:239], v159 offset:56320
	global_load_lds_dwordx4 v[154:155], off
	s_add_i32 m0, s48, 0x2000
	s_add_u32 s46, s46, 0x80080
	v_lshl_add_u64 v[154:155], v[176:177], 0, s[56:57]
	s_addc_u32 s47, s47, 0
	s_add_i32 s48, s77, s54
	global_load_lds_dwordx4 v[154:155], off
	v_lshl_add_u64 v[154:155], s[46:47], 0, v[136:137]
	s_mov_b32 m0, s48
	s_nop 0
	global_load_lds_dwordx4 v[154:155], off
	v_lshl_add_u64 v[154:155], s[46:47], 0, v[142:143]
	s_add_i32 m0, s48, 0x2000
	s_nop 0
	global_load_lds_dwordx4 v[154:155], off
	v_lshl_add_u64 v[154:155], v[202:203], 0, s[56:57]
	s_mov_b32 m0, s73
	s_nop 0
	global_load_lds_dwordx4 v[154:155], off
	v_lshl_add_u64 v[154:155], v[240:241], 0, s[56:57]
	s_mov_b32 m0, s74
	s_nop 0
	global_load_lds_dwordx4 v[154:155], off
	s_waitcnt vmcnt(8)
	s_waitcnt lgkmcnt(0)
	s_barrier
	s_setprio 1
	s_waitcnt lgkmcnt(0)
	v_mfma_f32_16x16x32_bf16 v[24:27], v[128:131], v[194:197], v[24:27]
	v_mfma_f32_16x16x32_bf16 v[28:31], v[150:153], v[194:197], v[28:31]
	v_mfma_f32_16x16x32_bf16 v[16:19], v[128:131], v[216:219], v[16:19]
	v_mfma_f32_16x16x32_bf16 v[20:23], v[150:153], v[216:219], v[20:23]
	v_mfma_f32_16x16x32_bf16 v[8:11], v[128:131], v[224:227], v[8:11]
	v_mfma_f32_16x16x32_bf16 v[12:15], v[150:153], v[224:227], v[12:15]
	v_mfma_f32_16x16x32_bf16 v[0:3], v[128:131], v[232:235], v[0:3]
	v_mfma_f32_16x16x32_bf16 v[4:7], v[150:153], v[232:235], v[4:7]
	v_mfma_f32_16x16x32_bf16 v[24:27], v[132:135], v[198:201], v[24:27]
	v_mfma_f32_16x16x32_bf16 v[28:31], v[160:163], v[198:201], v[28:31]
	v_mfma_f32_16x16x32_bf16 v[16:19], v[132:135], v[220:223], v[16:19]
	v_mfma_f32_16x16x32_bf16 v[20:23], v[160:163], v[220:223], v[20:23]
	v_mfma_f32_16x16x32_bf16 v[8:11], v[132:135], v[228:231], v[8:11]
	v_mfma_f32_16x16x32_bf16 v[12:15], v[160:163], v[228:231], v[12:15]
	v_mfma_f32_16x16x32_bf16 v[0:3], v[132:135], v[236:239], v[0:3]
	v_mfma_f32_16x16x32_bf16 v[4:7], v[160:163], v[236:239], v[4:7]
	s_setprio 0
	s_setprio 1
	v_mfma_f32_16x16x32_bf16 v[88:91], v[164:167], v[194:197], v[88:91]
	v_mfma_f32_16x16x32_bf16 v[92:95], v[172:175], v[194:197], v[92:95]
	v_mfma_f32_16x16x32_bf16 v[80:83], v[164:167], v[216:219], v[80:83]
	v_mfma_f32_16x16x32_bf16 v[84:87], v[172:175], v[216:219], v[84:87]
	v_mfma_f32_16x16x32_bf16 v[72:75], v[164:167], v[224:227], v[72:75]
	v_mfma_f32_16x16x32_bf16 v[76:79], v[172:175], v[224:227], v[76:79]
	v_mfma_f32_16x16x32_bf16 v[64:67], v[164:167], v[232:235], v[64:67]
	v_mfma_f32_16x16x32_bf16 v[68:71], v[172:175], v[232:235], v[68:71]
	v_mfma_f32_16x16x32_bf16 v[88:91], v[168:171], v[198:201], v[88:91]
	v_mfma_f32_16x16x32_bf16 v[92:95], v[190:193], v[198:201], v[92:95]
	v_mfma_f32_16x16x32_bf16 v[80:83], v[168:171], v[220:223], v[80:83]
	v_mfma_f32_16x16x32_bf16 v[84:87], v[190:193], v[220:223], v[84:87]
	v_mfma_f32_16x16x32_bf16 v[72:75], v[168:171], v[228:231], v[72:75]
	v_mfma_f32_16x16x32_bf16 v[76:79], v[190:193], v[228:231], v[76:79]
	v_mfma_f32_16x16x32_bf16 v[64:67], v[168:171], v[236:239], v[64:67]
	v_mfma_f32_16x16x32_bf16 v[68:71], v[190:193], v[236:239], v[68:71]
	s_setprio 0
	s_barrier
	s_add_i32 s51, s51, 2
	s_add_u32 s36, s36, 0x100
	s_addc_u32 s37, s37, 0
	s_add_u32 s45, s45, 0x100
	s_addc_u32 s50, s50, 0
	s_cmp_gt_u32 s51, 29
	s_cbranch_scc0 .LBB0_489
	s_and_b64 vcc, exec, s[20:21]
	s_cbranch_vccz .LBB0_492
	s_barrier

; __device__ __forceinline__ u32x4 pack8(const float* v) { u32x4 o; o[0] = pk2(v[0], v[1]); o[1] = pk2(v[2], v[3]); o[2] = pk2(v[4], v[5]); o[3] = pk2(v[6], v[7]); return o; }
; __device__ __forceinline__ float sigm(float x) { return __builtin_amdgcn_rcpf(1.f + __expf(-x)); }
;     __device__ __forceinline__ void operator()(const AccT& acc, const pg8::Unit& u, int wr, int wc, int fr, int fq) const {
;     ...
;                 bf16_t* rowp = base + (size_t)(row0 + ai * 128 + m * 16) * ldc + col0;
; #pragma unroll
;                 for (int bj = 0; bj < 2; ++bj) {
;                     float v[8];
; #pragma unroll
;                     for (int j = 0; j < 4; ++j) { v[j] = acc[ai][bj][m][0][j]; v[4 + j] = acc[ai][bj][m][1][j]; }
;                     if (op != 0) {
; #pragma unroll
;                         for (int j = 0; j < 8; ++j) { const float s = sigm(v[j]); v[j] = (op == 1) ? v[j] * s : s; }
;                     }
;                     *(u32x4*)(rowp + bj * 128) = pack8(v);
.LBB0_611:
	v_cvt_pk_bf16_f32 v64, v72, v73
	v_cvt_pk_bf16_f32 v65, v74, v75
	v_cvt_pk_bf16_f32 v66, v76, v77
	v_cvt_pk_bf16_f32 v67, v78, v79
	global_store_dwordx4 v[80:81], v[64:67], off offset:256
	s_mov_b32 s98, 1

; #define PG8_STAGE(bufoff, gbase, voff) do { _Pragma("unroll") for (int _i = 0; _i < 2; ++_i) \
;         __builtin_amdgcn_global_load_lds((const unsigned*)((const char*)(gbase) + (voff)[_i]), (LAS unsigned*)(lds + (bufoff) + ldsw + _i * 8192), 16, 0, 0); } while (0)
; #define PG8_BAR __builtin_amdgcn_s_barrier()
; template <class Epi>
; __device__ __forceinline__ void gemm_phase(LAS unsigned char* lds, const Gemm g, const StaticOrder& S, const Epi& E, const int tid) {
;     const int wid = __builtin_amdgcn_readfirstlane(tid >> 6), lane = tid & 63, wr = wid >> 2, wc = wid & 3, fr = lane & 15, fq = lane >> 4;
;     const int K = g.K, nt = K / BK;
;     unsigned voffA[2], voffB[2];
; #pragma unroll
;     for (int i = 0; i < 2; ++i) { int R, C; stage_rc(tid * 16 + i * 8192, R, C); const int Rb = Epi::PERM ? ((R & ~31) + perm32(R & 31)) : R;
;         voffA[i] = (unsigned)(R * g.lda + C) * 2u; voffB[i] = (unsigned)(Rb * g.ldb + C) * 2u; }
;     const size_t kstep = (size_t)(BK * 2);
;     const size_t hstepA = (size_t)HALF * g.lda * 2, hstepB = (size_t)HALF * g.ldb * 2;
;     const size_t tstepA = 2 * hstepA, tstepB = 2 * hstepB;
;     const unsigned ldsw = (unsigned)wid * 1024u;
;     const int aoff = lds_byte(wr * 64 + fr, fq * 8), boff = lds_byte(wc * 32 + fr, fq * 8);
;     ...
;     Unit cur, nxt; int ui = 0;
;     if (!S.next(0, cur)) return;
;     f32x4 acc[2][2][4][2];
; #pragma unroll
;     for (int a = 0; a < 2; ++a)
; #pragma unroll
;         for (int b = 0; b < 2; ++b)
; #pragma unroll
;             for (int m = 0; m < 4; ++m)
; #pragma unroll
;                 for (int n = 0; n < 2; ++n) acc[a][b][m][n] = (f32x4){0.f, 0.f, 0.f, 0.f};
;     bf16x8 At[4][2], B0[2][2], B1[2][2];
;     const char* cA = (const char*)g.A + (size_t)cur.pm * tstepA + (size_t)cur.half * K * 2; const char* cB = (const char*)g.Bt + (size_t)cur.pn * tstepB + (size_t)cur.half * K * 2;
;     PG8_STAGE(PG8_SB(0, 0), cB, voffB); PG8_STAGE(PG8_SB(0, 1), cB + hstepB, voffB); PG8_STAGE(PG8_SA(0, 0), cA, voffA); PG8_STAGE(PG8_SA(0, 1), cA + hstepA, voffA);
;     if (wr == 1) PG8_BAR;
.LBB0_714:
	v_readlane_b32 s2, v248, 12
	v_readlane_b32 s3, v248, 13
	s_andn2_b64 vcc, exec, s[2:3]
	v_readfirstlane_b32 s4, v188
	s_cbranch_vccnz .LBB0_798
	s_mov_b32 s98, 0
	v_lshlrev_b32_e32 v0, 4, v188
	v_add_u32_e32 v1, 0x2000, v0
	v_ashrrev_i32_e32 v2, 31, v1
	v_lshrrev_b32_e32 v2, 22, v2
	v_add_u32_e32 v2, v1, v2
	v_ashrrev_i32_e32 v8, 10, v2
	v_mul_i32_i24_e32 v3, 0x400, v8
	v_sub_u32_e32 v1, v1, v3
	v_lshrrev_b32_e32 v3, 4, v1
	v_bitop3_b32 v1, v3, v1, 32 bitop3:0x6c
	v_ashrrev_i32_e32 v3, 31, v1
	v_lshrrev_b32_e32 v3, 26, v3
	v_add_u32_e32 v3, v1, v3
	v_ashrrev_i32_e32 v9, 6, v3
	v_and_b32_e32 v3, 0xc0, v3
	v_sub_u32_e32 v1, v1, v3
	v_lshlrev_b32_e32 v2, 5, v8
	v_ashrrev_i16_sdwa v1, v208, sext(v1) dst_sel:DWORD dst_unused:UNUSED_PAD src0_sel:DWORD src1_sel:BYTE_0
	v_and_b32_e32 v2, 32, v2
	v_bfe_i32 v10, v1, 0, 16
	v_add_u32_e32 v1, v2, v10
	v_lshlrev_b32_e32 v2, 3, v8
	v_and_b32_e32 v2, 0xffff0, v2
	v_add_lshl_u32 v2, v9, v2, 12
	v_lshl_add_u32 v190, v1, 1, v2
	v_bfe_i32 v2, v188, 27, 1
	v_lshrrev_b32_e32 v2, 22, v2
	v_add_u32_e32 v2, v0, v2
	v_and_b32_e32 v2, 0xfffffc00, v2
	v_sub_u32_e32 v0, v0, v2
	v_lshrrev_b32_e32 v2, 4, v0
	v_bitop3_b32 v0, v2, v0, 32 bitop3:0x6c
	v_ashrrev_i32_e32 v2, 31, v0
	v_ashrrev_i32_e32 v1, 31, v188
	v_lshrrev_b32_e32 v2, 26, v2
	v_lshrrev_b32_e32 v1, 26, v1
	v_add_u32_e32 v2, v0, v2
	s_add_u32 s26, s8, 0xc200000
	v_add_u32_e32 v1, v188, v1
	v_ashrrev_i32_e32 v12, 6, v2
	v_and_b32_e32 v2, 0xc0, v2
	s_addc_u32 s27, s9, 0
	v_ashrrev_i32_e32 v11, 6, v1
	v_sub_u32_e32 v0, v0, v2
	s_add_u32 s28, s8, 0x3900000
	v_lshlrev_b32_e32 v1, 5, v11
	v_ashrrev_i16_sdwa v0, v208, sext(v0) dst_sel:DWORD dst_unused:UNUSED_PAD src0_sel:DWORD src1_sel:BYTE_0
	s_addc_u32 s29, s9, 0
	s_ashr_i32 s5, s4, 6
	v_and_b32_e32 v1, 32, v1
	v_bfe_i32 v13, v0, 0, 16
	s_ashr_i32 s8, s4, 8
	s_lshl_b32 s30, s5, 10
	v_add_u32_e32 v0, v1, v13
	v_lshlrev_b32_e32 v1, 3, v11
	v_readlane_b32 s2, v247, 18
	v_and_b32_e32 v1, 0xffff0, v1
	v_readlane_b32 s3, v247, 19
	s_add_u32 s20, s28, s2
	v_add_lshl_u32 v1, v12, v1, 12
	s_addc_u32 s21, s29, s3
	s_add_i32 s31, s30, 0
	v_lshl_add_u32 v192, v0, 1, v1
	s_add_i32 m0, s31, 0x10000
	v_mov_b32_e32 v193, v137
	global_load_lds_dwordx4 v192, s[20:21]
	s_add_i32 m0, s31, 0x12000
	s_add_u32 s2, s20, 0x80000
	global_load_lds_dwordx4 v190, s[20:21]
	s_addc_u32 s3, s21, 0
	s_add_i32 m0, s31, 0x14000
	v_mov_b32_e32 v191, v137
	global_load_lds_dwordx4 v192, s[2:3]
	s_add_i32 m0, s31, 0x16000
	v_lshl_add_u64 v[6:7], s[20:21], 0, v[192:193]
	global_load_lds_dwordx4 v190, s[2:3]
	v_readlane_b32 s2, v247, 22
	v_readlane_b32 s3, v247, 23
	s_add_u32 s6, s26, s2
	s_addc_u32 s7, s27, s3
	s_add_i32 s34, s31, 0x2000
	s_mov_b32 m0, s31
	s_add_u32 s2, s6, 0x80000
	global_load_lds_dwordx4 v192, s[6:7]
	s_mov_b32 m0, s34
	s_addc_u32 s3, s7, 0
	s_add_i32 s35, s31, 0x4000
	global_load_lds_dwordx4 v190, s[6:7]
	s_mov_b32 m0, s35
	s_add_i32 s36, s31, 0x6000
	global_load_lds_dwordx4 v192, s[2:3]
	s_mov_b32 m0, s36
	s_cmp_eq_u32 s8, 1
	global_load_lds_dwordx4 v190, s[2:3]
	v_lshl_add_u64 v[4:5], s[20:21], 0, v[190:191]
	v_lshl_add_u64 v[0:1], s[6:7], 0, v[192:193]
	s_cselect_b64 s[2:3], -1, 0
	s_cmp_lg_u32 s8, 1
	v_lshl_add_u64 v[2:3], s[6:7], 0, v[190:191]
	s_cbranch_scc1 .LBB0_717
	s_barrier

; #define PG8_STAGE(bufoff, gbase, voff) do { _Pragma("unroll") for (int _i = 0; _i < 2; ++_i) \
;         __builtin_amdgcn_global_load_lds((const unsigned*)((const char*)(gbase) + (voff)[_i]), (LAS unsigned*)(lds + (bufoff) + ldsw + _i * 8192), 16, 0, 0); } while (0)
; #define PG8_LDA(dst, b, h) do { _Pragma("unroll") for (int m = 0; m < 4; ++m) _Pragma("unroll") for (int k = 0; k < 2; ++k) dst[m][k] = *(const LAS bf16x8*)(lds + PG8_SA(b, h) + aoff + m * 2048 + k * 1024); } while (0)
; #define PG8_LDB(dst, b, h) do { _Pragma("unroll") for (int n = 0; n < 2; ++n) _Pragma("unroll") for (int k = 0; k < 2; ++k) dst[n][k] = *(const LAS bf16x8*)(lds + PG8_SB(b, h) + boff + n * 2048 + k * 1024); } while (0)
; #define PG8_MMA(ai, bj, At, Bt) do { __builtin_amdgcn_s_setprio(1); _Pragma("unroll") for (int m = 0; m < 4; ++m) _Pragma("unroll") for (int n = 0; n < 2; ++n) _Pragma("unroll") for (int k = 0; k < 2; ++k) \
;         acc[ai][bj][m][n] = __builtin_amdgcn_mfma_f32_16x16x32_bf16(Bt[n][k], At[m][k], acc[ai][bj][m][n], 0, 0, 0); __builtin_amdgcn_s_setprio(0); } while (0)
; #define PG8_WAIT_V(n) asm volatile("s_waitcnt vmcnt(" #n ")" ::: "memory")
; #define PG8_WAIT_L(n) asm volatile("s_waitcnt lgkmcnt(" #n ")" ::: "memory")
; #define PG8_BAR __builtin_amdgcn_s_barrier()
; #define PG8_SCHED __builtin_amdgcn_sched_barrier(0)
; template <class Epi>
; __device__ __forceinline__ void gemm_phase(LAS unsigned char* lds, const Gemm g, const StaticOrder& S, const Epi& E, const int tid) {
;     ...
;         for (int t = 0; t < nt; t += 2) {
;             const bool last = (t == nt - 2);
;             const char* a1 = cA + (size_t)(t + 1) * kstep;
;             const char* a2 = last ? nA : cA + (size_t)(t + 2) * kstep; const char* b2 = last ? nB : cB + (size_t)(t + 2) * kstep;
;             const char* a3 = a2 + kstep; const char* b3 = b2 + kstep;
;             PG8_LDB(B0, 0, 0); PG8_LDB(B1, 0, 1); PG8_SCHED; PG8_LDA(At, 0, 0); PG8_STAGE(PG8_SA(1, 1), a1 + hstepA, voffA);
;             PG8_WAIT_V(8); PG8_WAIT_L(0); PG8_BAR; PG8_MMA(0, 0, At, B0); PG8_MMA(0, 1, At, B1); PG8_BAR; PG8_SCHED;
;             PG8_LDA(At, 0, 1); PG8_STAGE(PG8_SB(0, 0), b2, voffB); PG8_STAGE(PG8_SB(0, 1), b2 + hstepB, voffB); PG8_STAGE(PG8_SA(0, 0), a2, voffA);
;             PG8_WAIT_V(8); PG8_WAIT_L(0); PG8_BAR; PG8_MMA(1, 0, At, B0); PG8_MMA(1, 1, At, B1); PG8_BAR; PG8_SCHED;
.LBB0_727:
	s_add_u32 s20, s6, 0xfff80080
	s_addc_u32 s21, s7, -1
	s_add_i32 s50, 0, 0x10000
	s_cmp_eq_u32 s49, 28
	s_cselect_b32 s25, s15, s21
	s_cselect_b32 s24, s45, s20
	s_cselect_b32 s21, s13, s48
	s_cselect_b32 s20, s46, s47
	s_add_i32 s52, 0, 0x14000
	v_add_u32_e32 v100, s50, v189
	v_add_u32_e32 v136, s52, v189
	ds_read_b128 v[88:91], v100
	ds_read_b128 v[92:95], v100 offset:1024
	ds_read_b128 v[96:99], v100 offset:2048
	ds_read_b128 v[100:103], v100 offset:3072
	ds_read_b128 v[146:149], v136
	ds_read_b128 v[150:153], v136 offset:1024
	ds_read_b128 v[154:157], v136 offset:2048
	ds_read_b128 v[158:161], v136 offset:3072
	v_lshl_add_u64 v[202:203], s[6:7], 0, v[194:195]
	s_add_i32 m0, s31, 0xc000
	ds_read_b128 v[162:165], v216
	ds_read_b128 v[166:169], v216 offset:1024
	ds_read_b128 v[170:173], v216 offset:2048
	ds_read_b128 v[174:177], v216 offset:3072
	ds_read_b128 v[198:201], v216 offset:4096
	ds_read_b128 v[218:221], v216 offset:5120
	ds_read_b128 v[222:225], v216 offset:6144
	ds_read_b128 v[226:229], v216 offset:7168
	global_load_lds_dwordx4 v[202:203], off
	v_lshl_add_u64 v[202:203], s[6:7], 0, v[196:197]
	s_add_i32 m0, s31, 0xe000
	s_nop 0
	global_load_lds_dwordx4 v[202:203], off
	s_cmp_lg_u32 s98, 0
	s_cbranch_scc1 .Ltb_g30r
	s_waitcnt vmcnt(8)
	s_branch .Ltb_g30d
.Ltb_g30r:
	s_waitcnt vmcnt(34)
.Ltb_g30d:
	s_waitcnt lgkmcnt(0)
	s_barrier
	s_setprio 1
	s_waitcnt lgkmcnt(0)
	v_mfma_f32_16x16x32_bf16 v[142:145], v[88:91], v[162:165], v[142:145]
	v_mfma_f32_16x16x32_bf16 v[138:141], v[96:99], v[162:165], v[138:141]
	v_mfma_f32_16x16x32_bf16 v[124:127], v[88:91], v[170:173], v[124:127]
	v_mfma_f32_16x16x32_bf16 v[120:123], v[96:99], v[170:173], v[120:123]
	v_mfma_f32_16x16x32_bf16 v[108:111], v[88:91], v[198:201], v[108:111]
	v_mfma_f32_16x16x32_bf16 v[104:107], v[96:99], v[198:201], v[104:107]
	v_mfma_f32_16x16x32_bf16 v[76:79], v[88:91], v[222:225], v[76:79]
	v_mfma_f32_16x16x32_bf16 v[72:75], v[96:99], v[222:225], v[72:75]
	v_mfma_f32_16x16x32_bf16 v[142:145], v[92:95], v[166:169], v[142:145]
	v_mfma_f32_16x16x32_bf16 v[138:141], v[100:103], v[166:169], v[138:141]
	v_mfma_f32_16x16x32_bf16 v[124:127], v[92:95], v[174:177], v[124:127]
	v_mfma_f32_16x16x32_bf16 v[120:123], v[100:103], v[174:177], v[120:123]
	v_mfma_f32_16x16x32_bf16 v[108:111], v[92:95], v[218:221], v[108:111]
	v_mfma_f32_16x16x32_bf16 v[104:107], v[100:103], v[218:221], v[104:107]
	v_mfma_f32_16x16x32_bf16 v[76:79], v[92:95], v[226:229], v[76:79]
	v_mfma_f32_16x16x32_bf16 v[72:75], v[100:103], v[226:229], v[72:75]
	s_setprio 0
	s_setprio 1
	v_mfma_f32_16x16x32_bf16 v[132:135], v[146:149], v[162:165], v[132:135]
	v_mfma_f32_16x16x32_bf16 v[128:131], v[154:157], v[162:165], v[128:131]
	v_mfma_f32_16x16x32_bf16 v[116:119], v[146:149], v[170:173], v[116:119]
	v_mfma_f32_16x16x32_bf16 v[112:115], v[154:157], v[170:173], v[112:115]
	v_mfma_f32_16x16x32_bf16 v[84:87], v[146:149], v[198:201], v[84:87]
	v_mfma_f32_16x16x32_bf16 v[80:83], v[154:157], v[198:201], v[80:83]
	v_mfma_f32_16x16x32_bf16 v[68:71], v[146:149], v[222:225], v[68:71]
	v_mfma_f32_16x16x32_bf16 v[64:67], v[154:157], v[222:225], v[64:67]
	v_mfma_f32_16x16x32_bf16 v[132:135], v[150:153], v[166:169], v[132:135]
	v_mfma_f32_16x16x32_bf16 v[128:131], v[158:161], v[166:169], v[128:131]
	v_mfma_f32_16x16x32_bf16 v[116:119], v[150:153], v[174:177], v[116:119]
	v_mfma_f32_16x16x32_bf16 v[112:115], v[158:161], v[174:177], v[112:115]
	v_mfma_f32_16x16x32_bf16 v[84:87], v[150:153], v[218:221], v[84:87]
	v_mfma_f32_16x16x32_bf16 v[80:83], v[158:161], v[218:221], v[80:83]
	v_mfma_f32_16x16x32_bf16 v[68:71], v[150:153], v[226:229], v[68:71]
	v_mfma_f32_16x16x32_bf16 v[64:67], v[158:161], v[226:229], v[64:67]
	s_setprio 0
	s_barrier
	s_add_i32 s50, s50, s30
	v_lshl_add_u64 v[202:203], s[20:21], 0, v[192:193]
	s_mov_b32 m0, s50
	ds_read_b128 v[162:165], v216 offset:16384
	ds_read_b128 v[166:169], v216 offset:17408
	ds_read_b128 v[170:173], v216 offset:18432
	ds_read_b128 v[174:177], v216 offset:19456
	ds_read_b128 v[198:201], v216 offset:20480
	ds_read_b128 v[218:221], v216 offset:21504
	ds_read_b128 v[222:225], v216 offset:22528
	ds_read_b128 v[226:229], v216 offset:23552
	global_load_lds_dwordx4 v[202:203], off
	s_add_i32 m0, s50, 0x2000
	s_add_u32 s50, s20, 0x80000
	v_lshl_add_u64 v[230:231], s[20:21], 0, v[190:191]
	s_addc_u32 s51, s21, 0
	s_add_i32 s52, s52, s30
	global_load_lds_dwordx4 v[230:231], off
	v_lshl_add_u64 v[232:233], s[50:51], 0, v[192:193]
	s_mov_b32 m0, s52
	v_lshl_add_u64 v[234:235], s[24:25], 0, v[190:191]
	global_load_lds_dwordx4 v[232:233], off
	v_lshl_add_u64 v[232:233], s[50:51], 0, v[190:191]
	s_add_i32 m0, s52, 0x2000
	s_nop 0
	global_load_lds_dwordx4 v[232:233], off
	v_lshl_add_u64 v[232:233], s[24:25], 0, v[192:193]
	s_mov_b32 m0, s31
	s_nop 0
	global_load_lds_dwordx4 v[232:233], off
	s_mov_b32 m0, s34
	s_nop 0
	global_load_lds_dwordx4 v[234:235], off
	s_cmp_lg_u32 s98, 0
	s_cbranch_scc1 .Ltb_g31r
	s_waitcnt vmcnt(8)
	s_branch .Ltb_g31d
.Ltb_g31r:
	s_waitcnt vmcnt(40)
; #define PG8_STAGE(bufoff, gbase, voff) do { _Pragma("unroll") for (int _i = 0; _i < 2; ++_i) \
;         __builtin_amdgcn_global_load_lds((const unsigned*)((const char*)(gbase) + (voff)[_i]), (LAS unsigned*)(lds + (bufoff) + ldsw + _i * 8192), 16, 0, 0); } while (0)
; #define PG8_LDA(dst, b, h) do { _Pragma("unroll") for (int m = 0; m < 4; ++m) _Pragma("unroll") for (int k = 0; k < 2; ++k) dst[m][k] = *(const LAS bf16x8*)(lds + PG8_SA(b, h) + aoff + m * 2048 + k * 1024); } while (0)
; #define PG8_LDB(dst, b, h) do { _Pragma("unroll") for (int n = 0; n < 2; ++n) _Pragma("unroll") for (int k = 0; k < 2; ++k) dst[n][k] = *(const LAS bf16x8*)(lds + PG8_SB(b, h) + boff + n * 2048 + k * 1024); } while (0)
; #define PG8_MMA(ai, bj, At, Bt) do { __builtin_amdgcn_s_setprio(1); _Pragma("unroll") for (int m = 0; m < 4; ++m) _Pragma("unroll") for (int n = 0; n < 2; ++n) _Pragma("unroll") for (int k = 0; k < 2; ++k) \
;         acc[ai][bj][m][n] = __builtin_amdgcn_mfma_f32_16x16x32_bf16(Bt[n][k], At[m][k], acc[ai][bj][m][n], 0, 0, 0); __builtin_amdgcn_s_setprio(0); } while (0)
; #define PG8_WAIT_V(n) asm volatile("s_waitcnt vmcnt(" #n ")" ::: "memory")
; #define PG8_WAIT_L(n) asm volatile("s_waitcnt lgkmcnt(" #n ")" ::: "memory")
; #define PG8_BAR __builtin_amdgcn_s_barrier()
; #define PG8_SCHED __builtin_amdgcn_sched_barrier(0)
; template <class Epi>
; __device__ __forceinline__ void gemm_phase(LAS unsigned char* lds, const Gemm g, const StaticOrder& S, const Epi& E, const int tid) {
;     ...
;             PG8_WAIT_V(8); PG8_WAIT_L(0); PG8_BAR; PG8_MMA(1, 0, At, B0); PG8_MMA(1, 1, At, B1); PG8_BAR; PG8_SCHED;
;             PG8_LDB(B0, 1, 0); PG8_LDB(B1, 1, 1); PG8_SCHED; PG8_LDA(At, 1, 0); PG8_STAGE(PG8_SA(0, 1), a2 + hstepA, voffA);
;             PG8_WAIT_V(8); PG8_WAIT_L(0); PG8_BAR; PG8_MMA(0, 0, At, B0); PG8_MMA(0, 1, At, B1); PG8_BAR; PG8_SCHED;
.Ltb_g31d:
	s_mov_b32 s98, 0
	s_waitcnt lgkmcnt(0)
	s_barrier
	s_setprio 1
	s_waitcnt lgkmcnt(0)
	v_mfma_f32_16x16x32_bf16 v[60:63], v[88:91], v[162:165], v[60:63]
	v_mfma_f32_16x16x32_bf16 v[56:59], v[96:99], v[162:165], v[56:59]
	v_mfma_f32_16x16x32_bf16 v[44:47], v[88:91], v[170:173], v[44:47]
	v_mfma_f32_16x16x32_bf16 v[40:43], v[96:99], v[170:173], v[40:43]
	v_mfma_f32_16x16x32_bf16 v[28:31], v[88:91], v[198:201], v[28:31]
	v_mfma_f32_16x16x32_bf16 v[24:27], v[96:99], v[198:201], v[24:27]
	v_mfma_f32_16x16x32_bf16 v[12:15], v[88:91], v[222:225], v[12:15]
	v_mfma_f32_16x16x32_bf16 v[8:11], v[96:99], v[222:225], v[8:11]
	v_mfma_f32_16x16x32_bf16 v[60:63], v[92:95], v[166:169], v[60:63]
	v_mfma_f32_16x16x32_bf16 v[56:59], v[100:103], v[166:169], v[56:59]
	v_mfma_f32_16x16x32_bf16 v[44:47], v[92:95], v[174:177], v[44:47]
	v_mfma_f32_16x16x32_bf16 v[40:43], v[100:103], v[174:177], v[40:43]
	v_mfma_f32_16x16x32_bf16 v[28:31], v[92:95], v[218:221], v[28:31]
	v_mfma_f32_16x16x32_bf16 v[24:27], v[100:103], v[218:221], v[24:27]
	v_mfma_f32_16x16x32_bf16 v[12:15], v[92:95], v[226:229], v[12:15]
	v_mfma_f32_16x16x32_bf16 v[8:11], v[100:103], v[226:229], v[8:11]
	s_setprio 0
	s_setprio 1
	v_mfma_f32_16x16x32_bf16 v[52:55], v[146:149], v[162:165], v[52:55]
	v_mfma_f32_16x16x32_bf16 v[48:51], v[154:157], v[162:165], v[48:51]
	v_mfma_f32_16x16x32_bf16 v[36:39], v[146:149], v[170:173], v[36:39]
	v_mfma_f32_16x16x32_bf16 v[32:35], v[154:157], v[170:173], v[32:35]
	v_mfma_f32_16x16x32_bf16 v[20:23], v[146:149], v[198:201], v[20:23]
	v_mfma_f32_16x16x32_bf16 v[16:19], v[154:157], v[198:201], v[16:19]
	v_mfma_f32_16x16x32_bf16 v[4:7], v[146:149], v[222:225], v[4:7]
	v_mfma_f32_16x16x32_bf16 v[0:3], v[154:157], v[222:225], v[0:3]
	v_mfma_f32_16x16x32_bf16 v[52:55], v[150:153], v[166:169], v[52:55]
	v_mfma_f32_16x16x32_bf16 v[48:51], v[158:161], v[166:169], v[48:51]
	v_mfma_f32_16x16x32_bf16 v[36:39], v[150:153], v[174:177], v[36:39]
	v_mfma_f32_16x16x32_bf16 v[32:35], v[158:161], v[174:177], v[32:35]
	v_mfma_f32_16x16x32_bf16 v[20:23], v[150:153], v[218:221], v[20:23]
	v_mfma_f32_16x16x32_bf16 v[16:19], v[158:161], v[218:221], v[16:19]
	v_mfma_f32_16x16x32_bf16 v[4:7], v[150:153], v[226:229], v[4:7]
	v_mfma_f32_16x16x32_bf16 v[0:3], v[158:161], v[226:229], v[0:3]
	s_setprio 0
	s_barrier
	s_add_i32 s50, 0, 0x18000
	s_add_i32 s51, 0, 0x1c000
	v_add_u32_e32 v100, s50, v189
	v_add_u32_e32 v136, s51, v189
	ds_read_b128 v[88:91], v100
	ds_read_b128 v[92:95], v100 offset:1024
	ds_read_b128 v[96:99], v100 offset:2048
	ds_read_b128 v[100:103], v100 offset:3072
	ds_read_b128 v[146:149], v136
	ds_read_b128 v[150:153], v136 offset:1024
	ds_read_b128 v[154:157], v136 offset:2048
	ds_read_b128 v[158:161], v136 offset:3072
	s_add_u32 s24, s24, 0x80000
	s_addc_u32 s25, s25, 0
	s_mov_b32 m0, s35
	v_lshl_add_u64 v[236:237], s[24:25], 0, v[192:193]
	ds_read_b128 v[162:165], v216 offset:32768
	ds_read_b128 v[166:169], v216 offset:33792
	ds_read_b128 v[170:173], v216 offset:34816
	ds_read_b128 v[174:177], v216 offset:35840
	ds_read_b128 v[198:201], v216 offset:36864
	ds_read_b128 v[218:221], v216 offset:37888
	ds_read_b128 v[222:225], v216 offset:38912
	ds_read_b128 v[226:229], v216 offset:39936
	global_load_lds_dwordx4 v[236:237], off
	v_lshl_add_u64 v[236:237], s[24:25], 0, v[190:191]
	s_mov_b32 m0, s36
	s_nop 0
	global_load_lds_dwordx4 v[236:237], off
	s_waitcnt vmcnt(8)
	s_waitcnt lgkmcnt(0)
	s_barrier
	s_setprio 1
	s_waitcnt lgkmcnt(0)
	v_mfma_f32_16x16x32_bf16 v[142:145], v[88:91], v[162:165], v[142:145]
	v_mfma_f32_16x16x32_bf16 v[138:141], v[96:99], v[162:165], v[138:141]
	v_mfma_f32_16x16x32_bf16 v[124:127], v[88:91], v[170:173], v[124:127]
	v_mfma_f32_16x16x32_bf16 v[120:123], v[96:99], v[170:173], v[120:123]
	v_mfma_f32_16x16x32_bf16 v[108:111], v[88:91], v[198:201], v[108:111]
	v_mfma_f32_16x16x32_bf16 v[104:107], v[96:99], v[198:201], v[104:107]
	v_mfma_f32_16x16x32_bf16 v[76:79], v[88:91], v[222:225], v[76:79]
	v_mfma_f32_16x16x32_bf16 v[72:75], v[96:99], v[222:225], v[72:75]
	v_mfma_f32_16x16x32_bf16 v[142:145], v[92:95], v[166:169], v[142:145]
	v_mfma_f32_16x16x32_bf16 v[138:141], v[100:103], v[166:169], v[138:141]
	v_mfma_f32_16x16x32_bf16 v[124:127], v[92:95], v[174:177], v[124:127]
	v_mfma_f32_16x16x32_bf16 v[120:123], v[100:103], v[174:177], v[120:123]
	v_mfma_f32_16x16x32_bf16 v[108:111], v[92:95], v[218:221], v[108:111]
	v_mfma_f32_16x16x32_bf16 v[104:107], v[100:103], v[218:221], v[104:107]
	v_mfma_f32_16x16x32_bf16 v[76:79], v[92:95], v[226:229], v[76:79]
	v_mfma_f32_16x16x32_bf16 v[72:75], v[100:103], v[226:229], v[72:75]
	s_setprio 0
	s_setprio 1
	v_mfma_f32_16x16x32_bf16 v[132:135], v[146:149], v[162:165], v[132:135]
	v_mfma_f32_16x16x32_bf16 v[128:131], v[154:157], v[162:165], v[128:131]
	v_mfma_f32_16x16x32_bf16 v[116:119], v[146:149], v[170:173], v[116:119]
	v_mfma_f32_16x16x32_bf16 v[112:115], v[154:157], v[170:173], v[112:115]
	v_mfma_f32_16x16x32_bf16 v[84:87], v[146:149], v[198:201], v[84:87]
	v_mfma_f32_16x16x32_bf16 v[80:83], v[154:157], v[198:201], v[80:83]
	v_mfma_f32_16x16x32_bf16 v[68:71], v[146:149], v[222:225], v[68:71]
	v_mfma_f32_16x16x32_bf16 v[64:67], v[154:157], v[222:225], v[64:67]
	v_mfma_f32_16x16x32_bf16 v[132:135], v[150:153], v[166:169], v[132:135]
	v_mfma_f32_16x16x32_bf16 v[128:131], v[158:161], v[166:169], v[128:131]
	v_mfma_f32_16x16x32_bf16 v[116:119], v[150:153], v[174:177], v[116:119]
	v_mfma_f32_16x16x32_bf16 v[112:115], v[158:161], v[174:177], v[112:115]
	v_mfma_f32_16x16x32_bf16 v[84:87], v[150:153], v[218:221], v[84:87]
	v_mfma_f32_16x16x32_bf16 v[80:83], v[158:161], v[218:221], v[80:83]
	v_mfma_f32_16x16x32_bf16 v[68:71], v[150:153], v[226:229], v[68:71]
	v_mfma_f32_16x16x32_bf16 v[64:67], v[158:161], v[226:229], v[64:67]
	s_setprio 0
	s_barrier
; #define PG8_STAGE(bufoff, gbase, voff) do { _Pragma("unroll") for (int _i = 0; _i < 2; ++_i) \
;         __builtin_amdgcn_global_load_lds((const unsigned*)((const char*)(gbase) + (voff)[_i]), (LAS unsigned*)(lds + (bufoff) + ldsw + _i * 8192), 16, 0, 0); } while (0)
; #define PG8_LDA(dst, b, h) do { _Pragma("unroll") for (int m = 0; m < 4; ++m) _Pragma("unroll") for (int k = 0; k < 2; ++k) dst[m][k] = *(const LAS bf16x8*)(lds + PG8_SA(b, h) + aoff + m * 2048 + k * 1024); } while (0)
; #define PG8_MMA(ai, bj, At, Bt) do { __builtin_amdgcn_s_setprio(1); _Pragma("unroll") for (int m = 0; m < 4; ++m) _Pragma("unroll") for (int n = 0; n < 2; ++n) _Pragma("unroll") for (int k = 0; k < 2; ++k) \
;         acc[ai][bj][m][n] = __builtin_amdgcn_mfma_f32_16x16x32_bf16(Bt[n][k], At[m][k], acc[ai][bj][m][n], 0, 0, 0); __builtin_amdgcn_s_setprio(0); } while (0)
; #define PG8_WAIT_V(n) asm volatile("s_waitcnt vmcnt(" #n ")" ::: "memory")
; #define PG8_WAIT_L(n) asm volatile("s_waitcnt lgkmcnt(" #n ")" ::: "memory")
; #define PG8_BAR __builtin_amdgcn_s_barrier()
; #define PG8_SCHED __builtin_amdgcn_sched_barrier(0)
; template <class Epi>
; __device__ __forceinline__ void gemm_phase(LAS unsigned char* lds, const Gemm g, const StaticOrder& S, const Epi& E, const int tid) {
;     ...
;             PG8_LDA(At, 1, 1); PG8_STAGE(PG8_SB(1, 0), b3, voffB); PG8_STAGE(PG8_SB(1, 1), b3 + hstepB, voffB); PG8_STAGE(PG8_SA(1, 0), a3, voffA);
;             PG8_WAIT_V(8); PG8_WAIT_L(0); PG8_BAR; PG8_MMA(1, 0, At, B0); PG8_MMA(1, 1, At, B1); PG8_BAR; PG8_SCHED;
;         }
;         if (wr == 0) PG8_BAR;
	s_add_i32 s24, s50, s30
	v_lshl_add_u64 v[202:203], v[202:203], 0, s[56:57]
	s_mov_b32 m0, s24
	ds_read_b128 v[162:165], v216 offset:49152
	ds_read_b128 v[166:169], v216 offset:50176
	ds_read_b128 v[170:173], v216 offset:51200
	ds_read_b128 v[174:177], v216 offset:52224
	ds_read_b128 v[198:201], v216 offset:53248
	ds_read_b128 v[218:221], v216 offset:54272
	ds_read_b128 v[222:225], v216 offset:55296
	ds_read_b128 v[226:229], v216 offset:56320
	global_load_lds_dwordx4 v[202:203], off
	s_add_i32 m0, s24, 0x2000
	s_add_u32 s20, s20, 0x80080
	v_lshl_add_u64 v[202:203], v[230:231], 0, s[56:57]
	s_addc_u32 s21, s21, 0
	s_add_i32 s24, s51, s30
	global_load_lds_dwordx4 v[202:203], off
	v_lshl_add_u64 v[202:203], s[20:21], 0, v[192:193]
	s_mov_b32 m0, s24
	s_nop 0
	global_load_lds_dwordx4 v[202:203], off
	v_lshl_add_u64 v[202:203], s[20:21], 0, v[190:191]
	s_add_i32 m0, s24, 0x2000
	s_nop 0
	global_load_lds_dwordx4 v[202:203], off
	v_lshl_add_u64 v[202:203], v[232:233], 0, s[56:57]
	s_mov_b32 m0, s40
	s_nop 0
	global_load_lds_dwordx4 v[202:203], off
	v_lshl_add_u64 v[202:203], v[234:235], 0, s[56:57]
	s_mov_b32 m0, s41
	s_nop 0
	global_load_lds_dwordx4 v[202:203], off
	s_waitcnt vmcnt(8)
	s_waitcnt lgkmcnt(0)
	s_barrier
	s_setprio 1
	s_waitcnt lgkmcnt(0)
	v_mfma_f32_16x16x32_bf16 v[60:63], v[88:91], v[162:165], v[60:63]
	v_mfma_f32_16x16x32_bf16 v[56:59], v[96:99], v[162:165], v[56:59]
	v_mfma_f32_16x16x32_bf16 v[44:47], v[88:91], v[170:173], v[44:47]
	v_mfma_f32_16x16x32_bf16 v[40:43], v[96:99], v[170:173], v[40:43]
	v_mfma_f32_16x16x32_bf16 v[28:31], v[88:91], v[198:201], v[28:31]
	v_mfma_f32_16x16x32_bf16 v[24:27], v[96:99], v[198:201], v[24:27]
	v_mfma_f32_16x16x32_bf16 v[12:15], v[88:91], v[222:225], v[12:15]
	v_mfma_f32_16x16x32_bf16 v[8:11], v[96:99], v[222:225], v[8:11]
	v_mfma_f32_16x16x32_bf16 v[60:63], v[92:95], v[166:169], v[60:63]
	v_mfma_f32_16x16x32_bf16 v[56:59], v[100:103], v[166:169], v[56:59]
	v_mfma_f32_16x16x32_bf16 v[44:47], v[92:95], v[174:177], v[44:47]
	v_mfma_f32_16x16x32_bf16 v[40:43], v[100:103], v[174:177], v[40:43]
	v_mfma_f32_16x16x32_bf16 v[28:31], v[92:95], v[218:221], v[28:31]
	v_mfma_f32_16x16x32_bf16 v[24:27], v[100:103], v[218:221], v[24:27]
	v_mfma_f32_16x16x32_bf16 v[12:15], v[92:95], v[226:229], v[12:15]
	v_mfma_f32_16x16x32_bf16 v[8:11], v[100:103], v[226:229], v[8:11]
	s_setprio 0
	s_setprio 1
	v_mfma_f32_16x16x32_bf16 v[52:55], v[146:149], v[162:165], v[52:55]
	v_mfma_f32_16x16x32_bf16 v[48:51], v[154:157], v[162:165], v[48:51]
	v_mfma_f32_16x16x32_bf16 v[36:39], v[146:149], v[170:173], v[36:39]
	v_mfma_f32_16x16x32_bf16 v[32:35], v[154:157], v[170:173], v[32:35]
	v_mfma_f32_16x16x32_bf16 v[20:23], v[146:149], v[198:201], v[20:23]
	v_mfma_f32_16x16x32_bf16 v[16:19], v[154:157], v[198:201], v[16:19]
	v_mfma_f32_16x16x32_bf16 v[4:7], v[146:149], v[222:225], v[4:7]
	v_mfma_f32_16x16x32_bf16 v[0:3], v[154:157], v[222:225], v[0:3]
	v_mfma_f32_16x16x32_bf16 v[52:55], v[150:153], v[166:169], v[52:55]
	v_mfma_f32_16x16x32_bf16 v[48:51], v[158:161], v[166:169], v[48:51]
	v_mfma_f32_16x16x32_bf16 v[36:39], v[150:153], v[174:177], v[36:39]
	v_mfma_f32_16x16x32_bf16 v[32:35], v[158:161], v[174:177], v[32:35]
	v_mfma_f32_16x16x32_bf16 v[20:23], v[150:153], v[218:221], v[20:23]
	v_mfma_f32_16x16x32_bf16 v[16:19], v[158:161], v[218:221], v[16:19]
	v_mfma_f32_16x16x32_bf16 v[4:7], v[150:153], v[226:229], v[4:7]
	v_mfma_f32_16x16x32_bf16 v[0:3], v[158:161], v[226:229], v[0:3]
	s_setprio 0
	s_barrier
	s_add_i32 s49, s49, 2
	s_add_u32 s6, s6, 0x100
	s_addc_u32 s7, s7, 0
	s_add_u32 s47, s47, 0x100
	s_addc_u32 s48, s48, 0
	s_cmp_gt_u32 s49, 29
	s_cbranch_scc0 .LBB0_727
	s_and_b64 vcc, exec, s[8:9]
	s_cbranch_vccz .LBB0_730
	s_barrier

; #define E3_LOAD(g_, B_) do { const float* xr_ = xrow(p, l, row0 + ((g_) >> 2) * 128 + ((g_) & 3) * 16) + col0; \
;             xb[B_][0][0] = *(const f32x4*)(xr_); xb[B_][0][1] = *(const f32x4*)(xr_ + 16); xb[B_][1][0] = *(const f32x4*)(xr_ + 128); xb[B_][1][1] = *(const f32x4*)(xr_ + 144); } while (0)
;     __device__ __forceinline__ void operator()(const AccT& acc, const pg8::Unit& u, int wr, int wc, int fr, int fq) const {
;     ...
;         E3_LOAD(0, 0);
; #pragma unroll
;         for (int g = 0; g < 8; ++g) {
;             const int ai = g >> 2, m = g & 3, B = g & 1;
;             if (g + 1 < 8) E3_LOAD(g + 1, B ^ 1);
;             float* yr = p.out + (size_t)(row0 + ai * 128 + m * 16) * DM + col0;
; #pragma unroll
;             for (int bj = 0; bj < 2; ++bj)
; #pragma unroll
;                 for (int n = 0; n < 2; ++n) *(f32x4*)(yr + bj * 128 + n * 16) = xb[B][bj][n] + gt[bj][n] * acc[ai][bj][m][n];
;         }
.LBB0_794:
	v_lshlrev_b64 v[36:37], 13, v[36:37]
	v_lshl_add_u64 v[34:35], v[34:35], 0, v[36:37]
	v_lshl_add_u64 v[46:47], v[34:35], 0, v[200:201]
	global_load_dwordx4 v[34:37], v[46:47], off
	global_load_dwordx4 v[38:41], v[46:47], off offset:64
	global_load_dwordx4 v[42:45], v[46:47], off offset:512
	global_load_dwordx4 v[64:67], v[46:47], off offset:576
	v_lshlrev_b64 v[46:47], 13, v[80:81]
	v_lshlrev_b64 v[32:33], 13, v[32:33]
	v_lshl_add_u64 v[46:47], s[90:91], 0, v[46:47]
	v_lshl_add_u64 v[32:33], s[90:91], 0, v[32:33]
	s_waitcnt vmcnt(11)
	v_pk_fma_f32 v[30:31], v[30:31], v[102:103], v[62:63]
	v_pk_fma_f32 v[28:29], v[28:29], v[100:101], v[60:61]
	v_lshl_add_u64 v[46:47], v[46:47], 0, v[200:201]
	v_lshl_add_u64 v[32:33], v[32:33], 0, v[200:201]
	s_andn2_b64 vcc, exec, s[4:5]
	s_mov_b64 s[4:5], -1
	s_waitcnt vmcnt(10)
	v_pk_fma_f32 v[26:27], v[26:27], v[98:99], v[58:59]
	v_pk_fma_f32 v[24:25], v[24:25], v[96:97], v[56:57]
	s_waitcnt vmcnt(9)
	v_pk_fma_f32 v[22:23], v[22:23], v[90:91], v[54:55]
	v_pk_fma_f32 v[20:21], v[20:21], v[88:89], v[52:53]
	s_waitcnt vmcnt(8)
	v_pk_fma_f32 v[18:19], v[18:19], v[94:95], v[50:51]
	v_pk_fma_f32 v[16:17], v[16:17], v[92:93], v[48:49]
	global_store_dwordx4 v[46:47], v[28:31], off
	global_store_dwordx4 v[46:47], v[24:27], off offset:64
	global_store_dwordx4 v[46:47], v[20:23], off offset:512
	global_store_dwordx4 v[46:47], v[16:19], off offset:576
	s_waitcnt vmcnt(7)
	v_pk_fma_f32 v[14:15], v[14:15], v[102:103], v[36:37]
	v_pk_fma_f32 v[12:13], v[12:13], v[100:101], v[34:35]
	s_waitcnt vmcnt(6)
	v_pk_fma_f32 v[10:11], v[10:11], v[98:99], v[40:41]
	v_pk_fma_f32 v[8:9], v[8:9], v[96:97], v[38:39]
	s_waitcnt vmcnt(5)
	v_pk_fma_f32 v[6:7], v[6:7], v[90:91], v[44:45]
	v_pk_fma_f32 v[4:5], v[4:5], v[88:89], v[42:43]
	s_waitcnt vmcnt(4)
	v_pk_fma_f32 v[2:3], v[2:3], v[94:95], v[66:67]
	v_pk_fma_f32 v[0:1], v[0:1], v[92:93], v[64:65]
	global_store_dwordx4 v[32:33], v[12:15], off
	global_store_dwordx4 v[32:33], v[8:11], off offset:64
	global_store_dwordx4 v[32:33], v[4:7], off offset:512
	global_store_dwordx4 v[32:33], v[0:3], off offset:576
	s_mov_b32 s98, 1
	s_cbranch_vccnz .LBB0_719
	s_andn2_b64 vcc, exec, s[2:3]
	s_cbranch_vccnz .LBB0_718
	s_barrier
	s_branch .LBB0_718
